# baseline (speedup 1.0000x reference)
; __device__ __forceinline__ unsigned pack2(float a, float b) { return (unsigned)f2bf(a) | ((unsigned)f2bf(b) << 16); }
; __device__ __forceinline__ void rmsnorm_phase(const float* __restrict__ xp_, const float* __restrict__ xs_, const float* __restrict__ g, u16* __restrict__ xn) {
;     ...
;   for (int r = gw; r < NRP; r += nw) {
;     u16* o = xn + (long)r * D;
;     if (r >= NR) {
; #pragma unroll
;       for (int i = 0; i < 8; ++i) *(uint2*)(o + (i * 64 + lane) * 4) = make_uint2(zz, zz);
;       continue;
;     }
;     const float* x = (r < NP) ? xp_ + (long)r * D : xs_ + (long)(r - NP) * D;
;     float4 v[8]; float ss = 0.f;
; #pragma unroll
;     for (int i = 0; i < 8; ++i) { v[i] = ((const float4*)x)[i * 64 + lane]; ss += v[i].x * v[i].x + v[i].y * v[i].y + v[i].z * v[i].z + v[i].w * v[i].w; }
;     ss = wave_sum(ss, lane);
;     const float rstd = rsqrtf(ss * (1.f / 2048.f) + EPS);
; #pragma unroll
;     for (int i = 0; i < 8; ++i) {
;       const float4 gg = gg8[i];
;       uint2 pk; pk.x = pack2(v[i].x * rstd * gg.x, v[i].y * rstd * gg.y); pk.y = pack2(v[i].z * rstd * gg.z, v[i].w * rstd * gg.w);
;       *(uint2*)(o + (i * 64 + lane) * 4) = pk;
;     }
;   }
.LBB0_144:
	s_or_b64 exec, exec, s[0:1]
	v_add_u32_e32 v46, s8, v46
	s_movk_i32 s0, 0x20ff
	v_cmp_lt_i32_e32 vcc, s0, v46
	global_store_dwordx2 v[58:59], v[38:39], off offset:1536 sc1
	v_lshl_add_u64 v[50:51], v[50:51], 0, s[12:13]
	s_or_b64 s[10:11], vcc, s[10:11]
	v_lshl_add_u64 v[58:59], v[58:59], 0, s[14:15]
	s_andn2_b64 exec, exec, s[10:11]
	s_cbranch_execz .LBB0_149
.LBB0_145:
	s_movk_i32 s0, 0x2080
	v_cmp_gt_i32_e32 vcc, s0, v46
	s_and_saveexec_b64 s[0:1], vcc
	s_xor_b64 s[20:21], exec, s[0:1]
	s_cbranch_execz .LBB0_147
	v_add_u32_e32 v2, 0xffffe000, v46
	v_lshlrev_b64 v[38:39], 13, v[2:3]
	s_movk_i32 s0, 0x2000
	v_lshl_add_u64 v[38:39], s[4:5], 0, v[38:39]
	v_cmp_gt_i32_e32 vcc, s0, v46
	v_mov_b32_e32 v49, v3
	v_mov_b32_e32 v53, v3
	v_cndmask_b32_e32 v39, v39, v51, vcc
	v_cndmask_b32_e32 v38, v38, v50, vcc
	v_mov_b32_e32 v55, v3
	v_lshl_add_u64 v[40:41], v[38:39], 0, v[48:49]
	v_lshl_add_u64 v[42:43], v[38:39], 0, v[52:53]
	v_lshl_add_u64 v[44:45], v[38:39], 0, v[54:55]
	global_load_dwordx4 v[64:67], v[40:41], off
	global_load_dwordx4 v[68:71], v[40:41], off offset:1024
	global_load_dwordx4 v[72:75], v[40:41], off offset:2048
	global_load_dwordx4 v[76:79], v[40:41], off offset:3072
	global_load_dwordx4 v[80:83], v[42:43], off
	s_nop 0
	global_load_dwordx4 v[42:45], v[44:45], off
	v_mov_b32_e32 v57, v3
	v_mov_b32_e32 v63, v3
	v_lshl_add_u64 v[40:41], v[38:39], 0, v[56:57]
	v_lshl_add_u64 v[38:39], v[38:39], 0, v[62:63]
	global_load_dwordx4 v[84:87], v[40:41], off
	s_nop 0
	global_load_dwordx4 v[38:41], v[38:39], off
	s_waitcnt vmcnt(7)
	v_mul_f32_e32 v2, v65, v65
	s_waitcnt vmcnt(6)
	v_mul_f32_e32 v49, v69, v69
	s_waitcnt vmcnt(5)
	v_mul_f32_e32 v53, v73, v73
	v_fmac_f32_e32 v2, v64, v64
	v_fmac_f32_e32 v49, v68, v68
	s_waitcnt vmcnt(4)
	v_mul_f32_e32 v55, v77, v77
	s_waitcnt vmcnt(3)
	v_mov_b32_e32 v90, v81
	s_waitcnt vmcnt(2)
	v_mov_b32_e32 v91, v43
	v_fmac_f32_e32 v53, v72, v72
	v_fmac_f32_e32 v2, v66, v66
	v_fmac_f32_e32 v49, v70, v70
	v_mov_b32_e32 v88, v80
	v_mov_b32_e32 v89, v42
	v_fmac_f32_e32 v55, v76, v76
	v_pk_mul_f32 v[90:91], v[90:91], v[90:91]
	v_fmac_f32_e32 v53, v74, v74
	v_fmac_f32_e32 v2, v67, v67
	v_fmac_f32_e32 v49, v71, v71
	v_mov_b32_e32 v92, v82
	v_mov_b32_e32 v93, v44
	s_waitcnt vmcnt(1)
	v_mov_b32_e32 v98, v85
	s_waitcnt vmcnt(0)
	v_mov_b32_e32 v99, v39
	v_fmac_f32_e32 v55, v78, v78
	v_pk_fma_f32 v[88:89], v[88:89], v[88:89], v[90:91]
	v_fmac_f32_e32 v53, v75, v75
	v_add_f32_e32 v2, v2, v49
	v_mov_b32_e32 v94, v83
	v_mov_b32_e32 v95, v45
	v_mov_b32_e32 v96, v84
	v_mov_b32_e32 v97, v38
	v_pk_mul_f32 v[98:99], v[98:99], v[98:99]
	v_fmac_f32_e32 v55, v79, v79
	v_pk_fma_f32 v[88:89], v[92:93], v[92:93], v[88:89]
	v_add_f32_e32 v2, v2, v53
	v_mov_b32_e32 v100, v86
	v_mov_b32_e32 v101, v40
	v_pk_fma_f32 v[90:91], v[96:97], v[96:97], v[98:99]
	v_pk_fma_f32 v[88:89], v[94:95], v[94:95], v[88:89]
	v_add_f32_e32 v2, v2, v55
	v_mov_b32_e32 v102, v87
	v_mov_b32_e32 v103, v41
	v_pk_fma_f32 v[90:91], v[100:101], v[100:101], v[90:91]
	v_add_f32_e32 v2, v2, v88
	v_pk_fma_f32 v[90:91], v[102:103], v[102:103], v[90:91]
	v_add_f32_e32 v2, v2, v89
	v_add_f32_e32 v2, v2, v90
	v_add_f32_e32 v2, v2, v91
	ds_swizzle_b32 v49, v2 offset:swizzle(SWAP,1)
	v_mov_b32_e32 v97, v82
	v_mov_b32_e32 v82, v42
	v_mov_b32_e32 v88, v64
	v_mov_b32_e32 v89, v66
	s_waitcnt lgkmcnt(0)
	v_add_f32_e32 v2, v2, v49
	ds_swizzle_b32 v49, v2 offset:swizzle(SWAP,2)
	v_mov_b32_e32 v66, v65
	v_mov_b32_e32 v90, v68
	v_mov_b32_e32 v91, v70
	v_mov_b32_e32 v96, v80
	s_waitcnt lgkmcnt(0)
	v_add_f32_e32 v2, v2, v49
	ds_swizzle_b32 v49, v2 offset:swizzle(SWAP,4)
	v_mov_b32_e32 v80, v81
	v_mov_b32_e32 v81, v83
	v_mov_b32_e32 v83, v44
	v_mov_b32_e32 v44, v43
	s_waitcnt lgkmcnt(0)
	v_add_f32_e32 v2, v2, v49
	ds_swizzle_b32 v49, v2 offset:swizzle(SWAP,8)
	v_mov_b32_e32 v70, v69
	v_mov_b32_e32 v93, v74
	v_mov_b32_e32 v74, v73
	v_mov_b32_e32 v92, v72
	s_waitcnt lgkmcnt(0)
	v_add_f32_e32 v2, v2, v49
	ds_swizzle_b32 v49, v2 offset:swizzle(SWAP,16)
	v_mov_b32_e32 v94, v76
	v_mov_b32_e32 v95, v78
	v_mov_b32_e32 v78, v77
	s_waitcnt lgkmcnt(0)
	v_add_f32_e32 v2, v2, v49
	ds_bpermute_b32 v49, v47, v2
	s_waitcnt lgkmcnt(0)
	v_add_f32_e32 v2, v2, v49
	v_fmamk_f32 v2, v2, 0x3a000000, v189
	v_mul_f32_e32 v42, 0x4b800000, v2
	v_cmp_gt_f32_e32 vcc, s62, v2
	s_nop 1
	v_cndmask_b32_e32 v2, v2, v42, vcc
	v_rsq_f32_e32 v2, v2
	s_nop 0
	v_mul_f32_e32 v42, 0x45800000, v2
	v_cndmask_b32_e32 v2, v2, v42, vcc
	v_pk_mul_f32 v[42:43], v[88:89], v[2:3] op_sel_hi:[1,0]
	v_pk_mul_f32 v[64:65], v[66:67], v[2:3] op_sel_hi:[1,0]
	v_pk_mul_f32 v[66:67], v[90:91], v[2:3] op_sel_hi:[1,0]
	v_pk_mul_f32 v[68:69], v[70:71], v[2:3] op_sel_hi:[1,0]
	v_pk_mul_f32 v[42:43], v[12:13], v[42:43]
	v_pk_mul_f32 v[64:65], v[10:11], v[64:65]
	v_pk_mul_f32 v[66:67], v[16:17], v[66:67]
	v_pk_mul_f32 v[68:69], v[14:15], v[68:69]
	v_and_b32_sdwa v49, v43, v226 dst_sel:DWORD dst_unused:UNUSED_PAD src0_sel:WORD_1 src1_sel:DWORD
	v_and_b32_sdwa v53, v42, v226 dst_sel:DWORD dst_unused:UNUSED_PAD src0_sel:WORD_1 src1_sel:DWORD
	v_and_b32_sdwa v55, v65, v226 dst_sel:DWORD dst_unused:UNUSED_PAD src0_sel:WORD_1 src1_sel:DWORD
	v_and_b32_sdwa v57, v64, v226 dst_sel:DWORD dst_unused:UNUSED_PAD src0_sel:WORD_1 src1_sel:DWORD
	v_pk_mul_f32 v[72:73], v[74:75], v[2:3] op_sel_hi:[1,0]
	v_and_b32_sdwa v63, v67, v226 dst_sel:DWORD dst_unused:UNUSED_PAD src0_sel:WORD_1 src1_sel:DWORD
	v_and_b32_sdwa v75, v69, v226 dst_sel:DWORD dst_unused:UNUSED_PAD src0_sel:WORD_1 src1_sel:DWORD
	v_and_b32_sdwa v76, v68, v226 dst_sel:DWORD dst_unused:UNUSED_PAD src0_sel:WORD_1 src1_sel:DWORD
	v_add3_u32 v42, v42, v53, s33
	v_add3_u32 v43, v43, v49, s33
; __device__ __forceinline__ unsigned pack2(float a, float b) { return (unsigned)f2bf(a) | ((unsigned)f2bf(b) << 16); }
; __device__ __forceinline__ void rmsnorm_phase(const float* __restrict__ xp_, const float* __restrict__ xs_, const float* __restrict__ g, u16* __restrict__ xn) {
;     ...
; #pragma unroll
;     for (int i = 0; i < 8; ++i) {
;       const float4 gg = gg8[i];
;       uint2 pk; pk.x = pack2(v[i].x * rstd * gg.x, v[i].y * rstd * gg.y); pk.y = pack2(v[i].z * rstd * gg.z, v[i].w * rstd * gg.w);
;       *(uint2*)(o + (i * 64 + lane) * 4) = pk;
;     }
	v_add3_u32 v49, v65, v55, s33
	v_add3_u32 v53, v64, v57, s33
	v_pk_mul_f32 v[70:71], v[92:93], v[2:3] op_sel_hi:[1,0]
	v_pk_mul_f32 v[72:73], v[18:19], v[72:73]
	v_and_b32_sdwa v74, v66, v226 dst_sel:DWORD dst_unused:UNUSED_PAD src0_sel:WORD_1 src1_sel:DWORD
	v_add3_u32 v57, v67, v63, s33
	v_add3_u32 v63, v69, v75, s33
	v_add3_u32 v64, v68, v76, s33
	v_and_b32_e32 v49, 0xffff0000, v49
	v_and_b32_e32 v53, 0xffff0000, v53
	v_pk_mul_f32 v[70:71], v[20:21], v[70:71]
	v_add3_u32 v55, v66, v74, s33
	v_and_b32_e32 v63, 0xffff0000, v63
	v_and_b32_e32 v64, 0xffff0000, v64
	v_or_b32_sdwa v43, v49, v43 dst_sel:DWORD dst_unused:UNUSED_PAD src0_sel:DWORD src1_sel:WORD_1
	v_or_b32_sdwa v42, v53, v42 dst_sel:DWORD dst_unused:UNUSED_PAD src0_sel:DWORD src1_sel:WORD_1
	v_and_b32_sdwa v49, v73, v226 dst_sel:DWORD dst_unused:UNUSED_PAD src0_sel:WORD_1 src1_sel:DWORD
	v_and_b32_sdwa v53, v72, v226 dst_sel:DWORD dst_unused:UNUSED_PAD src0_sel:WORD_1 src1_sel:DWORD
	v_and_b32_sdwa v77, v71, v226 dst_sel:DWORD dst_unused:UNUSED_PAD src0_sel:WORD_1 src1_sel:DWORD
	v_or_b32_sdwa v65, v63, v57 dst_sel:DWORD dst_unused:UNUSED_PAD src0_sel:DWORD src1_sel:WORD_1
	v_or_b32_sdwa v64, v64, v55 dst_sel:DWORD dst_unused:UNUSED_PAD src0_sel:DWORD src1_sel:WORD_1
	global_store_dwordx2 v[58:59], v[42:43], off offset:-2048 sc1
	global_store_dwordx2 v[58:59], v[64:65], off offset:-1536 sc1
	v_and_b32_sdwa v42, v70, v226 dst_sel:DWORD dst_unused:UNUSED_PAD src0_sel:WORD_1 src1_sel:DWORD
	v_add3_u32 v49, v73, v49, s33
	v_add3_u32 v53, v72, v53, s33
	v_add3_u32 v42, v70, v42, s33
	v_add3_u32 v43, v71, v77, s33
	v_and_b32_e32 v49, 0xffff0000, v49
	v_and_b32_e32 v53, 0xffff0000, v53
	v_or_b32_sdwa v43, v49, v43 dst_sel:DWORD dst_unused:UNUSED_PAD src0_sel:DWORD src1_sel:WORD_1
	v_or_b32_sdwa v42, v53, v42 dst_sel:DWORD dst_unused:UNUSED_PAD src0_sel:DWORD src1_sel:WORD_1
	global_store_dwordx2 v[58:59], v[42:43], off offset:-1024 sc1
	v_pk_mul_f32 v[42:43], v[94:95], v[2:3] op_sel_hi:[1,0]
	v_pk_mul_f32 v[64:65], v[78:79], v[2:3] op_sel_hi:[1,0]
	v_pk_mul_f32 v[42:43], v[24:25], v[42:43]
	v_pk_mul_f32 v[64:65], v[22:23], v[64:65]
	v_and_b32_sdwa v49, v43, v226 dst_sel:DWORD dst_unused:UNUSED_PAD src0_sel:WORD_1 src1_sel:DWORD
	v_and_b32_sdwa v53, v42, v226 dst_sel:DWORD dst_unused:UNUSED_PAD src0_sel:WORD_1 src1_sel:DWORD
	v_add3_u32 v42, v42, v53, s33
	v_add3_u32 v43, v43, v49, s33
	v_and_b32_sdwa v49, v65, v226 dst_sel:DWORD dst_unused:UNUSED_PAD src0_sel:WORD_1 src1_sel:DWORD
	v_and_b32_sdwa v53, v64, v226 dst_sel:DWORD dst_unused:UNUSED_PAD src0_sel:WORD_1 src1_sel:DWORD
	v_add3_u32 v49, v65, v49, s33
	v_add3_u32 v53, v64, v53, s33
	v_and_b32_e32 v49, 0xffff0000, v49
	v_and_b32_e32 v53, 0xffff0000, v53
	v_or_b32_sdwa v43, v49, v43 dst_sel:DWORD dst_unused:UNUSED_PAD src0_sel:DWORD src1_sel:WORD_1
	v_or_b32_sdwa v42, v53, v42 dst_sel:DWORD dst_unused:UNUSED_PAD src0_sel:DWORD src1_sel:WORD_1
	global_store_dwordx2 v[58:59], v[42:43], off offset:-512 sc1
	v_pk_mul_f32 v[42:43], v[96:97], v[2:3] op_sel_hi:[1,0]
	v_pk_mul_f32 v[64:65], v[80:81], v[2:3] op_sel_hi:[1,0]
	v_pk_mul_f32 v[42:43], v[28:29], v[42:43]
	v_pk_mul_f32 v[64:65], v[26:27], v[64:65]
	v_and_b32_sdwa v49, v43, v226 dst_sel:DWORD dst_unused:UNUSED_PAD src0_sel:WORD_1 src1_sel:DWORD
	v_and_b32_sdwa v53, v42, v226 dst_sel:DWORD dst_unused:UNUSED_PAD src0_sel:WORD_1 src1_sel:DWORD
	v_add3_u32 v42, v42, v53, s33
	v_add3_u32 v43, v43, v49, s33
	v_and_b32_sdwa v49, v65, v226 dst_sel:DWORD dst_unused:UNUSED_PAD src0_sel:WORD_1 src1_sel:DWORD
	v_and_b32_sdwa v53, v64, v226 dst_sel:DWORD dst_unused:UNUSED_PAD src0_sel:WORD_1 src1_sel:DWORD
	v_add3_u32 v49, v65, v49, s33
	v_add3_u32 v53, v64, v53, s33
	v_and_b32_e32 v49, 0xffff0000, v49
	v_and_b32_e32 v53, 0xffff0000, v53
	v_or_b32_sdwa v43, v49, v43 dst_sel:DWORD dst_unused:UNUSED_PAD src0_sel:DWORD src1_sel:WORD_1
; __device__ __forceinline__ unsigned pack2(float a, float b) { return (unsigned)f2bf(a) | ((unsigned)f2bf(b) << 16); }
; __device__ __forceinline__ void rmsnorm_phase(const float* __restrict__ xp_, const float* __restrict__ xs_, const float* __restrict__ g, u16* __restrict__ xn) {
;     ...
;     if (r >= NR) {
; #pragma unroll
;       for (int i = 0; i < 8; ++i) *(uint2*)(o + (i * 64 + lane) * 4) = make_uint2(zz, zz);
;       continue;
;     }
;     const float* x = (r < NP) ? xp_ + (long)r * D : xs_ + (long)(r - NP) * D;
;     float4 v[8]; float ss = 0.f;
; #pragma unroll
;     for (int i = 0; i < 8; ++i) { v[i] = ((const float4*)x)[i * 64 + lane]; ss += v[i].x * v[i].x + v[i].y * v[i].y + v[i].z * v[i].z + v[i].w * v[i].w; }
;     ss = wave_sum(ss, lane);
;     const float rstd = rsqrtf(ss * (1.f / 2048.f) + EPS);
; #pragma unroll
;     for (int i = 0; i < 8; ++i) {
;       const float4 gg = gg8[i];
;       uint2 pk; pk.x = pack2(v[i].x * rstd * gg.x, v[i].y * rstd * gg.y); pk.y = pack2(v[i].z * rstd * gg.z, v[i].w * rstd * gg.w);
;       *(uint2*)(o + (i * 64 + lane) * 4) = pk;
;     }
	v_or_b32_sdwa v42, v53, v42 dst_sel:DWORD dst_unused:UNUSED_PAD src0_sel:DWORD src1_sel:WORD_1
	global_store_dwordx2 v[58:59], v[42:43], off sc1
	v_pk_mul_f32 v[42:43], v[82:83], v[2:3] op_sel_hi:[1,0]
	v_pk_mul_f32 v[44:45], v[44:45], v[2:3] op_sel_hi:[1,0]
	v_pk_mul_f32 v[42:43], v[32:33], v[42:43]
	v_pk_mul_f32 v[44:45], v[30:31], v[44:45]
	v_and_b32_sdwa v49, v43, v226 dst_sel:DWORD dst_unused:UNUSED_PAD src0_sel:WORD_1 src1_sel:DWORD
	v_and_b32_sdwa v53, v42, v226 dst_sel:DWORD dst_unused:UNUSED_PAD src0_sel:WORD_1 src1_sel:DWORD
	v_add3_u32 v42, v42, v53, s33
	v_add3_u32 v43, v43, v49, s33
	v_and_b32_sdwa v49, v45, v226 dst_sel:DWORD dst_unused:UNUSED_PAD src0_sel:WORD_1 src1_sel:DWORD
	v_and_b32_sdwa v53, v44, v226 dst_sel:DWORD dst_unused:UNUSED_PAD src0_sel:WORD_1 src1_sel:DWORD
	v_add3_u32 v45, v45, v49, s33
	v_add3_u32 v44, v44, v53, s33
	v_and_b32_e32 v45, 0xffff0000, v45
	v_and_b32_e32 v44, 0xffff0000, v44
	v_or_b32_sdwa v43, v45, v43 dst_sel:DWORD dst_unused:UNUSED_PAD src0_sel:DWORD src1_sel:WORD_1
	v_or_b32_sdwa v42, v44, v42 dst_sel:DWORD dst_unused:UNUSED_PAD src0_sel:DWORD src1_sel:WORD_1
	global_store_dwordx2 v[58:59], v[42:43], off offset:512 sc1
	v_mov_b32_e32 v42, v84
	v_mov_b32_e32 v43, v86
	v_pk_mul_f32 v[42:43], v[42:43], v[2:3] op_sel_hi:[1,0]
	v_mov_b32_e32 v86, v85
	v_pk_mul_f32 v[42:43], v[36:37], v[42:43]
	v_pk_mul_f32 v[44:45], v[86:87], v[2:3] op_sel_hi:[1,0]
	v_and_b32_sdwa v49, v43, v226 dst_sel:DWORD dst_unused:UNUSED_PAD src0_sel:WORD_1 src1_sel:DWORD
	v_pk_mul_f32 v[44:45], v[34:35], v[44:45]
	v_and_b32_sdwa v53, v42, v226 dst_sel:DWORD dst_unused:UNUSED_PAD src0_sel:WORD_1 src1_sel:DWORD
	v_add3_u32 v42, v42, v53, s33
	v_add3_u32 v43, v43, v49, s33
	v_and_b32_sdwa v49, v45, v226 dst_sel:DWORD dst_unused:UNUSED_PAD src0_sel:WORD_1 src1_sel:DWORD
	v_and_b32_sdwa v53, v44, v226 dst_sel:DWORD dst_unused:UNUSED_PAD src0_sel:WORD_1 src1_sel:DWORD
	v_add3_u32 v45, v45, v49, s33
	v_add3_u32 v44, v44, v53, s33
	v_and_b32_e32 v45, 0xffff0000, v45
	v_and_b32_e32 v44, 0xffff0000, v44
	v_or_b32_sdwa v43, v45, v43 dst_sel:DWORD dst_unused:UNUSED_PAD src0_sel:DWORD src1_sel:WORD_1
	v_or_b32_sdwa v42, v44, v42 dst_sel:DWORD dst_unused:UNUSED_PAD src0_sel:DWORD src1_sel:WORD_1
	global_store_dwordx2 v[58:59], v[42:43], off offset:1024 sc1
	v_mov_b32_e32 v42, v38
	v_mov_b32_e32 v43, v40
	v_pk_mul_f32 v[42:43], v[42:43], v[2:3] op_sel_hi:[1,0]
	v_mov_b32_e32 v40, v39
	v_pk_mul_f32 v[42:43], v[8:9], v[42:43]
	v_pk_mul_f32 v[38:39], v[40:41], v[2:3] op_sel_hi:[1,0]
	v_and_b32_sdwa v40, v42, v226 dst_sel:DWORD dst_unused:UNUSED_PAD src0_sel:WORD_1 src1_sel:DWORD
	v_pk_mul_f32 v[38:39], v[60:61], v[38:39]
	v_add3_u32 v40, v42, v40, s33
	v_and_b32_sdwa v41, v39, v226 dst_sel:DWORD dst_unused:UNUSED_PAD src0_sel:WORD_1 src1_sel:DWORD
	v_and_b32_sdwa v42, v38, v226 dst_sel:DWORD dst_unused:UNUSED_PAD src0_sel:WORD_1 src1_sel:DWORD
	v_and_b32_sdwa v2, v43, v226 dst_sel:DWORD dst_unused:UNUSED_PAD src0_sel:WORD_1 src1_sel:DWORD
	v_add3_u32 v39, v39, v41, s33
	v_add3_u32 v38, v38, v42, s33
	v_add3_u32 v2, v43, v2, s33
	v_and_b32_e32 v39, 0xffff0000, v39
	v_and_b32_e32 v38, 0xffff0000, v38
	v_or_b32_sdwa v39, v39, v2 dst_sel:DWORD dst_unused:UNUSED_PAD src0_sel:DWORD src1_sel:WORD_1
	v_or_b32_sdwa v38, v38, v40 dst_sel:DWORD dst_unused:UNUSED_PAD src0_sel:DWORD src1_sel:WORD_1
.LBB0_147:
	s_andn2_saveexec_b64 s[0:1], s[20:21]
	s_cbranch_execz .LBB0_144
	v_mov_b64_e32 v[38:39], v[0:1]
	v_mov_b32_e32 v39, v0
	global_store_dwordx2 v[58:59], v[0:1], off offset:-2048 sc1
	global_store_dwordx2 v[58:59], v[0:1], off offset:-1536 sc1
	global_store_dwordx2 v[58:59], v[0:1], off offset:-1024 sc1
	global_store_dwordx2 v[58:59], v[0:1], off offset:-512 sc1
	global_store_dwordx2 v[58:59], v[0:1], off sc1
	global_store_dwordx2 v[58:59], v[0:1], off offset:512 sc1
	global_store_dwordx2 v[58:59], v[0:1], off offset:1024 sc1
	s_branch .LBB0_144

; template <int EPI>
; __device__ __forceinline__ void gemm_tile(const u16* __restrict__ A, long lda, const u16* __restrict__ Bt, long ldb, int K,
;                                           int brow, int bcol, const Epi& e, u16* shm) {
;     ...
; #pragma unroll
;     for (int ai = 0; ai < 2; ++ai) {
; #pragma unroll
;       for (int bj = 0; bj < 2; ++bj)
; #pragma unroll
;       for (int m = 0; m < 4; ++m)
; #pragma unroll
;       for (int n = 0; n < 2; ++n)
; #pragma unroll
;         for (int j = 0; j < 4; ++j) {
;           float v = acc[ai][bj][m][n][j];
;           if constexpr (EPI == EPI_FFN1) { v = fmaxf(v, 0.f); v = v * v; }
;           Cs[(wr * 64 + m * 16 + fq * 4 + j) * 264 + bj * HALF + wc * 32 + n * 16 + fr] = f2bf(v);
;         }
.LBB0_189:
	s_or_b64 exec, exec, s[0:1]
	v_mov_b32_e32 v137, v188
	s_waitcnt vmcnt(0)
	s_barrier
	s_movk_i32 s11, 0x210
	v_and_b32_e32 v0, 15, v137
	v_lshlrev_b32_e32 v140, 1, v0
	v_lshlrev_b32_e32 v0, 4, v137
	v_lshrrev_b32_e32 v1, 2, v137
	v_and_b32_e32 v2, 0x1f0, v0
	v_and_b32_e32 v138, 0xfffffcc, v1
	v_and_b32_e32 v1, 0xc0, v137
	v_add_u32_e32 v136, 0, v2
	v_ashrrev_i32_e32 v141, 5, v137
	v_add_u32_e32 v139, 0, v1
	v_mad_u64_u32 v[0:1], s[0:1], v141, s11, v[136:137]
	v_bfe_u32 v1, v132, 16, 1
	v_add3_u32 v1, v132, v1, s33
	v_mul_lo_u32 v132, v138, s11
	v_add3_u32 v132, v139, v140, v132
	ds_write_b16_d16_hi v132, v1
	v_bfe_u32 v1, v133, 16, 1
	v_add3_u32 v1, v133, v1, s33
	ds_write_b16_d16_hi v132, v1 offset:528
	v_bfe_u32 v1, v134, 16, 1
	v_add3_u32 v1, v134, v1, s33
	ds_write_b16_d16_hi v132, v1 offset:1056
	v_bfe_u32 v1, v135, 16, 1
	v_add3_u32 v1, v135, v1, s33
	ds_write_b16_d16_hi v132, v1 offset:1584
	v_bfe_u32 v1, v128, 16, 1
	v_add3_u32 v1, v128, v1, s33
	ds_write_b16_d16_hi v132, v1 offset:32
	v_bfe_u32 v1, v129, 16, 1
	v_add3_u32 v1, v129, v1, s33
	ds_write_b16_d16_hi v132, v1 offset:560
	v_bfe_u32 v1, v130, 16, 1
	v_add3_u32 v1, v130, v1, s33
	ds_write_b16_d16_hi v132, v1 offset:1088
	v_bfe_u32 v1, v131, 16, 1
	v_add3_u32 v1, v131, v1, s33
	ds_write_b16_d16_hi v132, v1 offset:1616
	v_bfe_u32 v1, v124, 16, 1
	v_add3_u32 v1, v124, v1, s33
	ds_write_b16_d16_hi v132, v1 offset:8448
	v_bfe_u32 v1, v125, 16, 1
	v_add3_u32 v1, v125, v1, s33
	ds_write_b16_d16_hi v132, v1 offset:8976
	v_bfe_u32 v1, v126, 16, 1
	v_add3_u32 v1, v126, v1, s33
	ds_write_b16_d16_hi v132, v1 offset:9504
	v_bfe_u32 v1, v127, 16, 1
	v_add3_u32 v1, v127, v1, s33
	ds_write_b16_d16_hi v132, v1 offset:10032
	v_bfe_u32 v1, v120, 16, 1
	v_add3_u32 v1, v120, v1, s33
	ds_write_b16_d16_hi v132, v1 offset:8480
	v_bfe_u32 v1, v121, 16, 1
	v_add3_u32 v1, v121, v1, s33
	ds_write_b16_d16_hi v132, v1 offset:9008
	v_bfe_u32 v1, v122, 16, 1
	v_add3_u32 v1, v122, v1, s33
	ds_write_b16_d16_hi v132, v1 offset:9536
	v_bfe_u32 v1, v123, 16, 1
	v_add3_u32 v1, v123, v1, s33
	ds_write_b16_d16_hi v132, v1 offset:10064
	v_bfe_u32 v1, v116, 16, 1
	v_add3_u32 v1, v116, v1, s33
	ds_write_b16_d16_hi v132, v1 offset:16896
	v_bfe_u32 v1, v117, 16, 1
	v_add3_u32 v1, v117, v1, s33
	ds_write_b16_d16_hi v132, v1 offset:17424
	v_bfe_u32 v1, v118, 16, 1
	v_add3_u32 v1, v118, v1, s33
	ds_write_b16_d16_hi v132, v1 offset:17952
	v_bfe_u32 v1, v119, 16, 1
	v_add3_u32 v1, v119, v1, s33
	ds_write_b16_d16_hi v132, v1 offset:18480
	v_bfe_u32 v1, v112, 16, 1
	v_add3_u32 v1, v112, v1, s33
	ds_write_b16_d16_hi v132, v1 offset:16928
	v_bfe_u32 v1, v113, 16, 1
	v_add3_u32 v1, v113, v1, s33
	ds_write_b16_d16_hi v132, v1 offset:17456
	v_bfe_u32 v1, v114, 16, 1
	v_add3_u32 v1, v114, v1, s33
	ds_write_b16_d16_hi v132, v1 offset:17984
	v_bfe_u32 v1, v115, 16, 1
	v_add3_u32 v1, v115, v1, s33
	ds_write_b16_d16_hi v132, v1 offset:18512
	v_bfe_u32 v1, v108, 16, 1
	v_add3_u32 v1, v108, v1, s33
	ds_write_b16_d16_hi v132, v1 offset:25344
	v_bfe_u32 v1, v109, 16, 1
	v_add3_u32 v1, v109, v1, s33
	ds_write_b16_d16_hi v132, v1 offset:25872
	v_bfe_u32 v1, v110, 16, 1
	v_add3_u32 v1, v110, v1, s33
	ds_write_b16_d16_hi v132, v1 offset:26400
	v_bfe_u32 v1, v111, 16, 1
	v_add3_u32 v1, v111, v1, s33
	ds_write_b16_d16_hi v132, v1 offset:26928
	v_bfe_u32 v1, v100, 16, 1
	v_add3_u32 v1, v100, v1, s33
	ds_write_b16_d16_hi v132, v1 offset:25376
	v_bfe_u32 v1, v101, 16, 1
	v_add3_u32 v1, v101, v1, s33
	ds_write_b16_d16_hi v132, v1 offset:25904
	v_bfe_u32 v1, v102, 16, 1
	v_add3_u32 v1, v102, v1, s33
	ds_write_b16_d16_hi v132, v1 offset:26432
	v_bfe_u32 v1, v103, 16, 1
	v_add3_u32 v1, v103, v1, s33
	ds_write_b16_d16_hi v132, v1 offset:26960
	v_bfe_u32 v1, v104, 16, 1
	v_add3_u32 v1, v104, v1, s33
	ds_write_b16_d16_hi v132, v1 offset:256
	v_bfe_u32 v1, v105, 16, 1
	v_add3_u32 v1, v105, v1, s33
	ds_write_b16_d16_hi v132, v1 offset:784
	v_bfe_u32 v1, v106, 16, 1
	v_add3_u32 v1, v106, v1, s33
	ds_write_b16_d16_hi v132, v1 offset:1312
	v_bfe_u32 v1, v107, 16, 1
	v_add3_u32 v1, v107, v1, s33
	ds_write_b16_d16_hi v132, v1 offset:1840
	v_bfe_u32 v1, v96, 16, 1
	v_add3_u32 v1, v96, v1, s33
	ds_write_b16_d16_hi v132, v1 offset:288
	v_bfe_u32 v1, v97, 16, 1
	v_add3_u32 v1, v97, v1, s33
	ds_write_b16_d16_hi v132, v1 offset:816
	v_bfe_u32 v1, v98, 16, 1
	v_add3_u32 v1, v98, v1, s33
	ds_write_b16_d16_hi v132, v1 offset:1344
	v_bfe_u32 v1, v99, 16, 1
	v_add3_u32 v1, v99, v1, s33
	ds_write_b16_d16_hi v132, v1 offset:1872
	v_bfe_u32 v1, v92, 16, 1
	v_add3_u32 v1, v92, v1, s33
	ds_write_b16_d16_hi v132, v1 offset:8704
	v_bfe_u32 v1, v93, 16, 1
	v_add3_u32 v1, v93, v1, s33
	ds_write_b16_d16_hi v132, v1 offset:9232
	v_bfe_u32 v1, v94, 16, 1
	v_add3_u32 v1, v94, v1, s33
	ds_write_b16_d16_hi v132, v1 offset:9760
	v_bfe_u32 v1, v95, 16, 1
	v_add3_u32 v1, v95, v1, s33
	ds_write_b16_d16_hi v132, v1 offset:10288
	v_bfe_u32 v1, v88, 16, 1
	v_add3_u32 v1, v88, v1, s33
	ds_write_b16_d16_hi v132, v1 offset:8736
	v_bfe_u32 v1, v89, 16, 1
	v_add3_u32 v1, v89, v1, s33
	ds_write_b16_d16_hi v132, v1 offset:9264
	v_bfe_u32 v1, v90, 16, 1
	v_add3_u32 v1, v90, v1, s33
	ds_write_b16_d16_hi v132, v1 offset:9792
	v_bfe_u32 v1, v91, 16, 1
	v_add3_u32 v1, v91, v1, s33
	ds_write_b16_d16_hi v132, v1 offset:10320
	v_bfe_u32 v1, v84, 16, 1
	v_add3_u32 v1, v84, v1, s33
	ds_write_b16_d16_hi v132, v1 offset:17152
	v_bfe_u32 v1, v85, 16, 1
	v_add3_u32 v1, v85, v1, s33
	ds_write_b16_d16_hi v132, v1 offset:17680
	v_bfe_u32 v1, v86, 16, 1
	v_add3_u32 v1, v86, v1, s33
	ds_write_b16_d16_hi v132, v1 offset:18208
	v_bfe_u32 v1, v87, 16, 1
	v_add3_u32 v1, v87, v1, s33
	ds_write_b16_d16_hi v132, v1 offset:18736
	v_bfe_u32 v1, v80, 16, 1
	v_add3_u32 v1, v80, v1, s33
	ds_write_b16_d16_hi v132, v1 offset:17184
	v_bfe_u32 v1, v81, 16, 1
	v_add3_u32 v1, v81, v1, s33
	ds_write_b16_d16_hi v132, v1 offset:17712
	v_bfe_u32 v1, v82, 16, 1
	v_add3_u32 v1, v82, v1, s33
	ds_write_b16_d16_hi v132, v1 offset:18240
	v_bfe_u32 v1, v83, 16, 1
	v_add3_u32 v1, v83, v1, s33
	ds_write_b16_d16_hi v132, v1 offset:18768
	v_bfe_u32 v1, v76, 16, 1
	v_add3_u32 v1, v76, v1, s33
	ds_write_b16_d16_hi v132, v1 offset:25600
	v_bfe_u32 v1, v77, 16, 1
	v_add3_u32 v1, v77, v1, s33
	ds_write_b16_d16_hi v132, v1 offset:26128
	v_bfe_u32 v1, v78, 16, 1
	v_add3_u32 v1, v78, v1, s33
	ds_write_b16_d16_hi v132, v1 offset:26656
	v_bfe_u32 v1, v79, 16, 1
	v_add3_u32 v1, v79, v1, s33
	ds_write_b16_d16_hi v132, v1 offset:27184
	v_bfe_u32 v1, v72, 16, 1
	v_add3_u32 v1, v72, v1, s33
	ds_write_b16_d16_hi v132, v1 offset:25632
	v_bfe_u32 v1, v73, 16, 1
	v_add3_u32 v1, v73, v1, s33
	ds_write_b16_d16_hi v132, v1 offset:26160
	v_bfe_u32 v1, v74, 16, 1
	v_add3_u32 v1, v74, v1, s33
	ds_write_b16_d16_hi v132, v1 offset:26688
	v_bfe_u32 v1, v75, 16, 1
	v_add3_u32 v1, v75, v1, s33
	ds_write_b16_d16_hi v132, v1 offset:27216
	v_add_u32_e32 v1, s26, v141
	v_mov_b64_e32 v[72:73], s[8:9]
	s_waitcnt lgkmcnt(0)
	s_barrier
; template <int EPI>
; __device__ __forceinline__ void gemm_tile(const u16* __restrict__ A, long lda, const u16* __restrict__ Bt, long ldb, int K,
;                                           int brow, int bcol, const Epi& e, u16* shm) {
;     ...
;       __syncthreads();
; #pragma unroll
;       for (int i = 0; i < 8; ++i) {
;         const int idx = tx + 512 * i, rl = idx >> 5, cv = idx & 31;
;         typedef __attribute__((ext_vector_type(4))) unsigned u32x4;
;         const u32x4 v = *(const u32x4*)(Cs + rl * 264 + cv * 8);
;         __builtin_nontemporal_store(v, (u32x4*)(e.cb + (long)(brow + ai * HALF + rl) * ldc + bcol + cv * 8));
;       }
	ds_read_b128 v[76:79], v0
	v_mad_i64_i32 v[74:75], s[0:1], v1, s31, v[72:73]
	s_lshl_b64 s[12:13], s[12:13], 1
	v_add_u32_e32 v1, 0x200, v137
	v_lshl_add_u64 v[74:75], v[74:75], 0, s[12:13]
	v_ashrrev_i32_e32 v98, 5, v1
	v_lshl_add_u64 v[84:85], v[74:75], 0, v[2:3]
	v_mad_u64_u32 v[74:75], s[0:1], v98, s11, v[136:137]
	ds_read_b128 v[80:83], v74
	v_add_u32_e32 v1, s26, v98
	s_waitcnt lgkmcnt(1)
	global_store_dwordx4 v[84:85], v[76:79], off sc1
	s_movk_i32 s63, 0x210
	s_nop 0
	v_mad_i64_i32 v[76:77], s[0:1], v1, s31, v[72:73]
	v_lshl_add_u64 v[76:77], v[76:77], 0, s[12:13]
	v_add_u32_e32 v1, 0x400, v137
	v_lshl_add_u64 v[76:77], v[76:77], 0, v[2:3]
	v_ashrrev_i32_e32 v75, 5, v1
	s_waitcnt lgkmcnt(0)
	global_store_dwordx4 v[76:77], v[80:83], off sc1
	v_mad_u64_u32 v[76:77], s[0:1], v75, s11, v[136:137]
	v_add_u32_e32 v1, s26, v75
	ds_read_b128 v[80:83], v76
	v_mad_i64_i32 v[78:79], s[0:1], v1, s31, v[72:73]
	v_add_u32_e32 v1, 0x600, v137
	v_lshl_add_u64 v[78:79], v[78:79], 0, s[12:13]
	v_ashrrev_i32_e32 v77, 5, v1
	v_lshl_add_u64 v[88:89], v[78:79], 0, v[2:3]
	v_mad_u64_u32 v[78:79], s[0:1], v77, s11, v[136:137]
	ds_read_b128 v[84:87], v78
	v_add_u32_e32 v1, s26, v77
	s_waitcnt lgkmcnt(1)
	global_store_dwordx4 v[88:89], v[80:83], off sc1
	s_nop 1
	v_mad_i64_i32 v[80:81], s[0:1], v1, s31, v[72:73]
	v_lshl_add_u64 v[80:81], v[80:81], 0, s[12:13]
	v_add_u32_e32 v1, 0x800, v137
	v_lshl_add_u64 v[80:81], v[80:81], 0, v[2:3]
	v_ashrrev_i32_e32 v79, 5, v1
	s_waitcnt lgkmcnt(0)
	global_store_dwordx4 v[80:81], v[84:87], off sc1
	v_mad_u64_u32 v[80:81], s[0:1], v79, s11, v[136:137]
	v_add_u32_e32 v1, s26, v79
	ds_read_b128 v[84:87], v80
	v_mad_i64_i32 v[82:83], s[0:1], v1, s31, v[72:73]
	v_add_u32_e32 v1, 0xa00, v137
	v_lshl_add_u64 v[82:83], v[82:83], 0, s[12:13]
	v_ashrrev_i32_e32 v81, 5, v1
	v_lshl_add_u64 v[92:93], v[82:83], 0, v[2:3]
	v_mad_u64_u32 v[82:83], s[0:1], v81, s11, v[136:137]
	ds_read_b128 v[88:91], v82
	v_add_u32_e32 v1, s26, v81
	s_waitcnt lgkmcnt(1)
	global_store_dwordx4 v[92:93], v[84:87], off sc1
	s_nop 1
	v_mad_i64_i32 v[84:85], s[0:1], v1, s31, v[72:73]
	v_lshl_add_u64 v[84:85], v[84:85], 0, s[12:13]
	v_add_u32_e32 v1, 0xc00, v137
	v_lshl_add_u64 v[84:85], v[84:85], 0, v[2:3]
	v_ashrrev_i32_e32 v83, 5, v1
	s_waitcnt lgkmcnt(0)
	global_store_dwordx4 v[84:85], v[88:91], off sc1
	v_mad_u64_u32 v[84:85], s[0:1], v83, s11, v[136:137]
	v_add_u32_e32 v1, s26, v83
	ds_read_b128 v[86:89], v84
	v_mad_i64_i32 v[90:91], s[0:1], v1, s31, v[72:73]
	v_add_u32_e32 v1, 0xe00, v137
	v_ashrrev_i32_e32 v85, 5, v1
	v_lshl_add_u64 v[90:91], v[90:91], 0, s[12:13]
	v_mad_u64_u32 v[96:97], s[0:1], v85, s11, v[136:137]
	v_lshl_add_u64 v[94:95], v[90:91], 0, v[2:3]
	ds_read_b128 v[90:93], v96
	v_add_u32_e32 v1, s26, v85
	s_waitcnt lgkmcnt(1)
	global_store_dwordx4 v[94:95], v[86:89], off sc1
	s_nop 1
	v_mad_i64_i32 v[86:87], s[0:1], v1, s31, v[72:73]
	v_lshl_add_u64 v[86:87], v[86:87], 0, s[12:13]
	v_bfe_u32 v1, v68, 16, 1
	v_lshl_add_u64 v[86:87], v[86:87], 0, v[2:3]
	v_add3_u32 v1, v68, v1, s33
	s_waitcnt lgkmcnt(0)
	global_store_dwordx4 v[86:87], v[90:93], off sc1
	s_barrier
	ds_write_b16_d16_hi v132, v1
	v_bfe_u32 v1, v69, 16, 1
	v_add3_u32 v1, v69, v1, s33
	ds_write_b16_d16_hi v132, v1 offset:528
	v_bfe_u32 v1, v70, 16, 1
	v_add3_u32 v1, v70, v1, s33
	ds_write_b16_d16_hi v132, v1 offset:1056
	v_bfe_u32 v1, v71, 16, 1
	v_add3_u32 v1, v71, v1, s33
	ds_write_b16_d16_hi v132, v1 offset:1584
	v_bfe_u32 v1, v64, 16, 1
	v_add3_u32 v1, v64, v1, s33
	ds_write_b16_d16_hi v132, v1 offset:32
	v_bfe_u32 v1, v65, 16, 1
	v_add3_u32 v1, v65, v1, s33
	ds_write_b16_d16_hi v132, v1 offset:560
	v_bfe_u32 v1, v66, 16, 1
	v_add3_u32 v1, v66, v1, s33
	ds_write_b16_d16_hi v132, v1 offset:1088
	v_bfe_u32 v1, v67, 16, 1
	v_add3_u32 v1, v67, v1, s33
	ds_write_b16_d16_hi v132, v1 offset:1616
	v_bfe_u32 v1, v60, 16, 1
	v_add3_u32 v1, v60, v1, s33
	ds_write_b16_d16_hi v132, v1 offset:8448
	v_bfe_u32 v1, v61, 16, 1
	v_add3_u32 v1, v61, v1, s33
	ds_write_b16_d16_hi v132, v1 offset:8976
	v_bfe_u32 v1, v62, 16, 1
	v_add3_u32 v1, v62, v1, s33
	ds_write_b16_d16_hi v132, v1 offset:9504
	v_bfe_u32 v1, v63, 16, 1
	v_add3_u32 v1, v63, v1, s33
	ds_write_b16_d16_hi v132, v1 offset:10032
	v_bfe_u32 v1, v56, 16, 1
	v_add3_u32 v1, v56, v1, s33
	ds_write_b16_d16_hi v132, v1 offset:8480
	v_bfe_u32 v1, v57, 16, 1
	v_add3_u32 v1, v57, v1, s33
	ds_write_b16_d16_hi v132, v1 offset:9008
	v_bfe_u32 v1, v58, 16, 1
	v_add3_u32 v1, v58, v1, s33
	ds_write_b16_d16_hi v132, v1 offset:9536
	v_bfe_u32 v1, v59, 16, 1
	v_add3_u32 v1, v59, v1, s33
	ds_write_b16_d16_hi v132, v1 offset:10064
	v_bfe_u32 v1, v52, 16, 1
	v_add3_u32 v1, v52, v1, s33
	ds_write_b16_d16_hi v132, v1 offset:16896
	v_bfe_u32 v1, v53, 16, 1
	v_add3_u32 v1, v53, v1, s33
	ds_write_b16_d16_hi v132, v1 offset:17424
	v_bfe_u32 v1, v54, 16, 1
	v_add3_u32 v1, v54, v1, s33
	ds_write_b16_d16_hi v132, v1 offset:17952
	v_bfe_u32 v1, v55, 16, 1
	v_add3_u32 v1, v55, v1, s33
	ds_write_b16_d16_hi v132, v1 offset:18480
	v_bfe_u32 v1, v48, 16, 1
	v_add3_u32 v1, v48, v1, s33
	ds_write_b16_d16_hi v132, v1 offset:16928
	v_bfe_u32 v1, v49, 16, 1
	v_add3_u32 v1, v49, v1, s33
	ds_write_b16_d16_hi v132, v1 offset:17456
	v_bfe_u32 v1, v50, 16, 1
	v_add3_u32 v1, v50, v1, s33
	ds_write_b16_d16_hi v132, v1 offset:17984
	v_bfe_u32 v1, v51, 16, 1
	v_add3_u32 v1, v51, v1, s33
	ds_write_b16_d16_hi v132, v1 offset:18512
	v_bfe_u32 v1, v44, 16, 1
	v_add3_u32 v1, v44, v1, s33
	ds_write_b16_d16_hi v132, v1 offset:25344
	v_bfe_u32 v1, v45, 16, 1
	v_add3_u32 v1, v45, v1, s33
	ds_write_b16_d16_hi v132, v1 offset:25872
	v_bfe_u32 v1, v46, 16, 1
	v_add3_u32 v1, v46, v1, s33
; template <int EPI>
; __device__ __forceinline__ void gemm_tile(const u16* __restrict__ A, long lda, const u16* __restrict__ Bt, long ldb, int K,
;                                           int brow, int bcol, const Epi& e, u16* shm) {
;     ...
; #pragma unroll
;     for (int ai = 0; ai < 2; ++ai) {
; #pragma unroll
;       for (int bj = 0; bj < 2; ++bj)
; #pragma unroll
;       for (int m = 0; m < 4; ++m)
; #pragma unroll
;       for (int n = 0; n < 2; ++n)
; #pragma unroll
;         for (int j = 0; j < 4; ++j) {
;           float v = acc[ai][bj][m][n][j];
;           if constexpr (EPI == EPI_FFN1) { v = fmaxf(v, 0.f); v = v * v; }
;           Cs[(wr * 64 + m * 16 + fq * 4 + j) * 264 + bj * HALF + wc * 32 + n * 16 + fr] = f2bf(v);
;         }
;       __syncthreads();
; #pragma unroll
;       for (int i = 0; i < 8; ++i) {
;         const int idx = tx + 512 * i, rl = idx >> 5, cv = idx & 31;
;         typedef __attribute__((ext_vector_type(4))) unsigned u32x4;
;         const u32x4 v = *(const u32x4*)(Cs + rl * 264 + cv * 8);
;         __builtin_nontemporal_store(v, (u32x4*)(e.cb + (long)(brow + ai * HALF + rl) * ldc + bcol + cv * 8));
;       }
;       __syncthreads();
	ds_write_b16_d16_hi v132, v1 offset:26400
	v_bfe_u32 v1, v47, 16, 1
	v_add3_u32 v1, v47, v1, s33
	ds_write_b16_d16_hi v132, v1 offset:26928
	v_bfe_u32 v1, v40, 16, 1
	v_add3_u32 v1, v40, v1, s33
	ds_write_b16_d16_hi v132, v1 offset:25376
	v_bfe_u32 v1, v41, 16, 1
	v_add3_u32 v1, v41, v1, s33
	ds_write_b16_d16_hi v132, v1 offset:25904
	v_bfe_u32 v1, v42, 16, 1
	v_add3_u32 v1, v42, v1, s33
	ds_write_b16_d16_hi v132, v1 offset:26432
	v_bfe_u32 v1, v43, 16, 1
	v_add3_u32 v1, v43, v1, s33
	ds_write_b16_d16_hi v132, v1 offset:26960
	v_bfe_u32 v1, v36, 16, 1
	v_add3_u32 v1, v36, v1, s33
	ds_write_b16_d16_hi v132, v1 offset:256
	v_bfe_u32 v1, v37, 16, 1
	v_add3_u32 v1, v37, v1, s33
	ds_write_b16_d16_hi v132, v1 offset:784
	v_bfe_u32 v1, v38, 16, 1
	v_add3_u32 v1, v38, v1, s33
	ds_write_b16_d16_hi v132, v1 offset:1312
	v_bfe_u32 v1, v39, 16, 1
	v_add3_u32 v1, v39, v1, s33
	ds_write_b16_d16_hi v132, v1 offset:1840
	v_bfe_u32 v1, v32, 16, 1
	v_add3_u32 v1, v32, v1, s33
	ds_write_b16_d16_hi v132, v1 offset:288
	v_bfe_u32 v1, v33, 16, 1
	v_add3_u32 v1, v33, v1, s33
	ds_write_b16_d16_hi v132, v1 offset:816
	v_bfe_u32 v1, v34, 16, 1
	v_add3_u32 v1, v34, v1, s33
	ds_write_b16_d16_hi v132, v1 offset:1344
	v_bfe_u32 v1, v35, 16, 1
	v_add3_u32 v1, v35, v1, s33
	ds_write_b16_d16_hi v132, v1 offset:1872
	v_bfe_u32 v1, v28, 16, 1
	v_add3_u32 v1, v28, v1, s33
	ds_write_b16_d16_hi v132, v1 offset:8704
	v_bfe_u32 v1, v29, 16, 1
	v_add3_u32 v1, v29, v1, s33
	ds_write_b16_d16_hi v132, v1 offset:9232
	v_bfe_u32 v1, v30, 16, 1
	v_add3_u32 v1, v30, v1, s33
	ds_write_b16_d16_hi v132, v1 offset:9760
	v_bfe_u32 v1, v31, 16, 1
	v_add3_u32 v1, v31, v1, s33
	ds_write_b16_d16_hi v132, v1 offset:10288
	v_bfe_u32 v1, v24, 16, 1
	v_add3_u32 v1, v24, v1, s33
	ds_write_b16_d16_hi v132, v1 offset:8736
	v_bfe_u32 v1, v25, 16, 1
	v_add3_u32 v1, v25, v1, s33
	ds_write_b16_d16_hi v132, v1 offset:9264
	v_bfe_u32 v1, v26, 16, 1
	v_add3_u32 v1, v26, v1, s33
	ds_write_b16_d16_hi v132, v1 offset:9792
	v_bfe_u32 v1, v27, 16, 1
	v_add3_u32 v1, v27, v1, s33
	ds_write_b16_d16_hi v132, v1 offset:10320
	v_bfe_u32 v1, v20, 16, 1
	v_add3_u32 v1, v20, v1, s33
	ds_write_b16_d16_hi v132, v1 offset:17152
	v_bfe_u32 v1, v21, 16, 1
	v_add3_u32 v1, v21, v1, s33
	ds_write_b16_d16_hi v132, v1 offset:17680
	v_bfe_u32 v1, v22, 16, 1
	v_add3_u32 v1, v22, v1, s33
	ds_write_b16_d16_hi v132, v1 offset:18208
	v_bfe_u32 v1, v23, 16, 1
	v_add3_u32 v1, v23, v1, s33
	ds_write_b16_d16_hi v132, v1 offset:18736
	v_bfe_u32 v1, v16, 16, 1
	v_add3_u32 v1, v16, v1, s33
	ds_write_b16_d16_hi v132, v1 offset:17184
	v_bfe_u32 v1, v17, 16, 1
	v_add3_u32 v1, v17, v1, s33
	ds_write_b16_d16_hi v132, v1 offset:17712
	v_bfe_u32 v1, v18, 16, 1
	v_add3_u32 v1, v18, v1, s33
	ds_write_b16_d16_hi v132, v1 offset:18240
	v_bfe_u32 v1, v19, 16, 1
	v_add3_u32 v1, v19, v1, s33
	ds_write_b16_d16_hi v132, v1 offset:18768
	v_bfe_u32 v1, v12, 16, 1
	v_add3_u32 v1, v12, v1, s33
	ds_write_b16_d16_hi v132, v1 offset:25600
	v_bfe_u32 v1, v13, 16, 1
	v_add3_u32 v1, v13, v1, s33
	ds_write_b16_d16_hi v132, v1 offset:26128
	v_bfe_u32 v1, v14, 16, 1
	v_add3_u32 v1, v14, v1, s33
	ds_write_b16_d16_hi v132, v1 offset:26656
	v_bfe_u32 v1, v15, 16, 1
	v_add3_u32 v1, v15, v1, s33
	ds_write_b16_d16_hi v132, v1 offset:27184
	v_bfe_u32 v1, v8, 16, 1
	v_add3_u32 v1, v8, v1, s33
	ds_write_b16_d16_hi v132, v1 offset:25632
	v_bfe_u32 v1, v9, 16, 1
	v_add3_u32 v1, v9, v1, s33
	ds_write_b16_d16_hi v132, v1 offset:26160
	v_bfe_u32 v1, v10, 16, 1
	v_add3_u32 v1, v10, v1, s33
	ds_write_b16_d16_hi v132, v1 offset:26688
	v_bfe_u32 v1, v11, 16, 1
	v_add3_u32 v1, v11, v1, s33
	ds_write_b16_d16_hi v132, v1 offset:27216
	s_waitcnt lgkmcnt(0)
	s_barrier
	ds_read_b128 v[8:11], v0
	ds_read_b128 v[12:15], v74
	v_add_u32_e32 v0, s10, v141
	v_mad_i64_i32 v[0:1], s[0:1], v0, s31, v[72:73]
	v_lshl_add_u64 v[0:1], v[0:1], 0, s[12:13]
	v_lshl_add_u64 v[0:1], v[0:1], 0, v[2:3]
	s_waitcnt lgkmcnt(1)
	global_store_dwordx4 v[0:1], v[8:11], off sc1
	v_add_u32_e32 v0, s10, v98
	v_mad_i64_i32 v[0:1], s[0:1], v0, s31, v[72:73]
	v_lshl_add_u64 v[0:1], v[0:1], 0, s[12:13]
	v_lshl_add_u64 v[0:1], v[0:1], 0, v[2:3]
	ds_read_b128 v[8:11], v76
	s_waitcnt lgkmcnt(1)
	global_store_dwordx4 v[0:1], v[12:15], off sc1
	v_add_u32_e32 v0, s10, v75
	v_mad_i64_i32 v[0:1], s[0:1], v0, s31, v[72:73]
	v_lshl_add_u64 v[0:1], v[0:1], 0, s[12:13]
	v_lshl_add_u64 v[0:1], v[0:1], 0, v[2:3]
	ds_read_b128 v[12:15], v78
	s_waitcnt lgkmcnt(1)
	global_store_dwordx4 v[0:1], v[8:11], off sc1
	v_add_u32_e32 v0, s10, v77
	v_mad_i64_i32 v[0:1], s[0:1], v0, s31, v[72:73]
	v_lshl_add_u64 v[0:1], v[0:1], 0, s[12:13]
	v_lshl_add_u64 v[0:1], v[0:1], 0, v[2:3]
	ds_read_b128 v[8:11], v80
	s_waitcnt lgkmcnt(1)
	global_store_dwordx4 v[0:1], v[12:15], off sc1
	v_add_u32_e32 v0, s10, v79
	v_mad_i64_i32 v[0:1], s[0:1], v0, s31, v[72:73]
	v_lshl_add_u64 v[0:1], v[0:1], 0, s[12:13]
	v_lshl_add_u64 v[0:1], v[0:1], 0, v[2:3]
	ds_read_b128 v[12:15], v82
	s_waitcnt lgkmcnt(1)
	global_store_dwordx4 v[0:1], v[8:11], off sc1
	v_add_u32_e32 v0, s10, v81
	v_mad_i64_i32 v[0:1], s[0:1], v0, s31, v[72:73]
	v_lshl_add_u64 v[0:1], v[0:1], 0, s[12:13]
	v_lshl_add_u64 v[0:1], v[0:1], 0, v[2:3]
	ds_read_b128 v[8:11], v84
	s_waitcnt lgkmcnt(1)
	global_store_dwordx4 v[0:1], v[12:15], off sc1
	v_add_u32_e32 v0, s10, v83
	v_mad_i64_i32 v[0:1], s[0:1], v0, s31, v[72:73]
	v_lshl_add_u64 v[0:1], v[0:1], 0, s[12:13]
	v_lshl_add_u64 v[0:1], v[0:1], 0, v[2:3]
	ds_read_b128 v[12:15], v96
	s_waitcnt lgkmcnt(1)
	global_store_dwordx4 v[0:1], v[8:11], off sc1
	v_add_u32_e32 v0, s10, v85
	v_mad_i64_i32 v[0:1], s[0:1], v0, s31, v[72:73]
	v_lshl_add_u64 v[0:1], v[0:1], 0, s[12:13]
	v_lshl_add_u64 v[0:1], v[0:1], 0, v[2:3]
	v_readlane_b32 s0, v252, 2
	s_waitcnt lgkmcnt(0)
	global_store_dwordx4 v[0:1], v[12:15], off sc1
	s_barrier
	s_add_i32 s58, s0, s58
	s_cmpk_gt_i32 s58, 0xbfc
	s_cbranch_scc1 .LBB0_204

; __device__ __forceinline__ unsigned pack2(float a, float b) { return (unsigned)f2bf(a) | ((unsigned)f2bf(b) << 16); }
; __device__ __forceinline__ void scan_phase(KP P, int l) {
;     ...
;     for (int c0 = 0; c0 < 64; c0 += 16) {
;       uint2 sv[16]; float d[16];
; #pragma unroll
;       for (int i = 0; i < 16; ++i) { sv[i] = *(const uint2*)(base + (long)(c0 + i) * 32 * 8192); d[i] = CD[(b * 64 + c0 + i) * 32 + h]; }
; #pragma unroll
;       for (int i = 0; i < 16; ++i) {
;         uint2 o; o.x = pack2(hc0, hc1); o.y = pack2(hc2, hc3);
;         *(uint2*)(base + (long)(c0 + i) * 32 * 8192) = o;
;         hc0 = hc0 * d[i] + __uint_as_float(sv[i].x << 16); hc1 = hc1 * d[i] + __uint_as_float(sv[i].x & 0xffff0000u);
;         hc2 = hc2 * d[i] + __uint_as_float(sv[i].y << 16); hc3 = hc3 * d[i] + __uint_as_float(sv[i].y & 0xffff0000u);
.LBB0_879:
	v_lshl_add_u64 v[8:9], v[14:15], 0, s[6:7]
	s_waitcnt vmcnt(14)
	v_add_co_u32_e32 v28, vcc, 0x45064000, v8
	v_lshl_add_u64 v[10:11], v[12:13], 0, s[6:7]
	s_nop 0
	v_addc_co_u32_e32 v29, vcc, 0, v9, vcc
	s_mov_b32 s1, 0x4d064000
	v_add_co_u32_e32 v30, vcc, s1, v10
	v_and_b32_sdwa v20, v17, v226 dst_sel:DWORD dst_unused:UNUSED_PAD src0_sel:WORD_1 src1_sel:DWORD
	s_nop 0
	v_addc_co_u32_e32 v31, vcc, 0, v11, vcc
	s_waitcnt vmcnt(8)
	v_add_co_u32_e32 v54, vcc, 0x450e4000, v8
	v_and_b32_sdwa v22, v16, v226 dst_sel:DWORD dst_unused:UNUSED_PAD src0_sel:WORD_1 src1_sel:DWORD
	s_nop 0
	v_addc_co_u32_e32 v55, vcc, 0, v9, vcc
	v_add_co_u32_e32 v56, vcc, 0x45164000, v8
	v_and_b32_sdwa v1, v19, v226 dst_sel:DWORD dst_unused:UNUSED_PAD src0_sel:WORD_1 src1_sel:DWORD
	s_nop 0
	v_addc_co_u32_e32 v57, vcc, 0, v9, vcc
	v_add_co_u32_e32 v72, vcc, 0x451e4000, v8
	v_and_b32_sdwa v2, v18, v226 dst_sel:DWORD dst_unused:UNUSED_PAD src0_sel:WORD_1 src1_sel:DWORD
	s_nop 0
	v_addc_co_u32_e32 v73, vcc, 0, v9, vcc
	v_add_co_u32_e32 v78, vcc, 0x45264000, v8
	v_add3_u32 v20, v17, v20, s33
	s_nop 0
	v_addc_co_u32_e32 v79, vcc, 0, v9, vcc
	v_add3_u32 v22, v16, v22, s33
	v_add_co_u32_e32 v80, vcc, 0x452e4000, v8
	v_add3_u32 v2, v18, v2, s33
	v_add3_u32 v1, v19, v1, s33
	v_and_b32_e32 v10, 0xffff0000, v20
	v_and_b32_e32 v20, 0xffff0000, v22
	global_load_dwordx2 v[52:53], v[28:29], off
	v_addc_co_u32_e32 v81, vcc, 0, v9, vcc
	v_or_b32_sdwa v33, v10, v1 dst_sel:DWORD dst_unused:UNUSED_PAD src0_sel:DWORD src1_sel:WORD_1
	v_or_b32_sdwa v32, v20, v2 dst_sel:DWORD dst_unused:UNUSED_PAD src0_sel:DWORD src1_sel:WORD_1
	v_add_co_u32_e32 v86, vcc, 0x45364000, v8
	global_load_dword v58, v[30:31], off
	global_load_dword v60, v[30:31], off offset:128
	global_load_dword v62, v[30:31], off offset:256
	global_load_dword v64, v[30:31], off offset:384
	global_load_dword v66, v[30:31], off offset:512
	global_load_dword v68, v[30:31], off offset:640
	global_load_dword v70, v[30:31], off offset:768
	global_load_dword v48, v[30:31], off offset:896
	global_load_dword v40, v[30:31], off offset:1024
	global_load_dword v38, v[30:31], off offset:1152
	global_load_dword v26, v[30:31], off offset:1280
	global_load_dword v24, v[30:31], off offset:1408
	global_load_dword v22, v[30:31], off offset:1536
	global_load_dword v20, v[30:31], off offset:1664
	global_load_dword v10, v[30:31], off offset:1792
	global_load_dword v2, v[30:31], off offset:1920
	v_addc_co_u32_e32 v87, vcc, 0, v9, vcc
	global_store_dwordx2 v[28:29], v[32:33], off sc1
	global_load_dwordx2 v[74:75], v[54:55], off
	global_load_dwordx2 v[76:77], v[56:57], off
	v_add_co_u32_e32 v50, vcc, 0x453e4000, v8
	global_load_dwordx2 v[82:83], v[72:73], off
	global_load_dwordx2 v[84:85], v[78:79], off
	v_addc_co_u32_e32 v51, vcc, 0, v9, vcc
	v_add_co_u32_e32 v46, vcc, 0x45464000, v8
	global_load_dwordx2 v[88:89], v[80:81], off
	global_load_dwordx2 v[90:91], v[86:87], off
	v_addc_co_u32_e32 v47, vcc, 0, v9, vcc
	v_add_co_u32_e32 v44, vcc, 0x454e4000, v8
	global_load_dwordx2 v[92:93], v[50:51], off
	global_load_dwordx2 v[94:95], v[46:47], off
	v_addc_co_u32_e32 v45, vcc, 0, v9, vcc
	v_add_co_u32_e32 v42, vcc, 0x45564000, v8
	s_mov_b64 s[18:19], 0x800
	s_nop 0
	v_addc_co_u32_e32 v43, vcc, 0, v9, vcc
	v_add_co_u32_e32 v34, vcc, 0x455e4000, v8
	global_load_dwordx2 v[96:97], v[44:45], off
	global_load_dwordx2 v[98:99], v[42:43], off
	v_addc_co_u32_e32 v35, vcc, 0, v9, vcc
	v_add_co_u32_e32 v30, vcc, 0x45664000, v8
	v_lshl_add_u64 v[12:13], v[12:13], 0, s[18:19]
	s_nop 0
	v_addc_co_u32_e32 v31, vcc, 0, v9, vcc
	v_add_co_u32_e32 v28, vcc, 0x456e4000, v8
	global_load_dwordx2 v[100:101], v[34:35], off
	global_load_dwordx2 v[102:103], v[30:31], off
	v_addc_co_u32_e32 v29, vcc, 0, v9, vcc
	v_add_co_u32_e32 v32, vcc, 0x45764000, v8
	global_load_dwordx2 v[104:105], v[28:29], off
	s_nop 0
	v_addc_co_u32_e32 v33, vcc, 0, v9, vcc
	v_add_co_u32_e32 v36, vcc, 0x457e4000, v8
	s_add_i32 s0, s0, 16
	s_nop 0
	v_addc_co_u32_e32 v37, vcc, 0, v9, vcc
	global_load_dwordx2 v[8:9], v[32:33], off
	global_load_dwordx2 v[106:107], v[36:37], off
	s_mov_b64 s[18:19], 0x800000
	v_lshl_add_u64 v[14:15], v[14:15], 0, s[18:19]
	s_cmp_gt_u32 s0, 47
	s_waitcnt vmcnt(32)
	v_lshlrev_b32_e32 v109, 16, v53
	v_lshlrev_b32_e32 v108, 16, v52
	v_and_b32_e32 v53, 0xffff0000, v53
	v_and_b32_e32 v52, 0xffff0000, v52
	s_waitcnt vmcnt(31)
	v_pk_fma_f32 v[16:17], v[16:17], v[58:59], v[52:53] op_sel_hi:[1,0,1]
	v_pk_fma_f32 v[18:19], v[18:19], v[58:59], v[108:109] op_sel_hi:[1,0,1]
	v_and_b32_sdwa v25, v17, v226 dst_sel:DWORD dst_unused:UNUSED_PAD src0_sel:WORD_1 src1_sel:DWORD
	v_and_b32_sdwa v27, v16, v226 dst_sel:DWORD dst_unused:UNUSED_PAD src0_sel:WORD_1 src1_sel:DWORD
	v_and_b32_sdwa v1, v19, v226 dst_sel:DWORD dst_unused:UNUSED_PAD src0_sel:WORD_1 src1_sel:DWORD
	v_and_b32_sdwa v11, v18, v226 dst_sel:DWORD dst_unused:UNUSED_PAD src0_sel:WORD_1 src1_sel:DWORD
	s_waitcnt vmcnt(14)
	v_and_b32_e32 v59, 0xffff0000, v75
	v_and_b32_e32 v58, 0xffff0000, v74
	v_lshlrev_b32_e32 v53, 16, v75
	v_lshlrev_b32_e32 v52, 16, v74
	v_add3_u32 v25, v17, v25, s33
	v_add3_u32 v27, v16, v27, s33
	v_pk_fma_f32 v[16:17], v[60:61], v[16:17], v[58:59] op_sel_hi:[0,1,1]
	s_waitcnt vmcnt(13)
	v_and_b32_e32 v59, 0xffff0000, v77
	v_and_b32_e32 v58, 0xffff0000, v76
	v_add3_u32 v11, v18, v11, s33
	v_add3_u32 v1, v19, v1, s33
	v_pk_fma_f32 v[18:19], v[60:61], v[18:19], v[52:53] op_sel_hi:[0,1,1]
	v_lshlrev_b32_e32 v53, 16, v77
	v_lshlrev_b32_e32 v52, 16, v76
	v_and_b32_e32 v27, 0xffff0000, v27
	v_and_b32_sdwa v65, v16, v226 dst_sel:DWORD dst_unused:UNUSED_PAD src0_sel:WORD_1 src1_sel:DWORD
	v_pk_fma_f32 v[58:59], v[62:63], v[16:17], v[58:59] op_sel_hi:[0,1,1]
	v_and_b32_e32 v25, 0xffff0000, v25
	v_and_b32_sdwa v49, v17, v226 dst_sel:DWORD dst_unused:UNUSED_PAD src0_sel:WORD_1 src1_sel:DWORD
	v_pk_fma_f32 v[52:53], v[62:63], v[18:19], v[52:53] op_sel_hi:[0,1,1]
	s_waitcnt vmcnt(12)
; __device__ __forceinline__ unsigned pack2(float a, float b) { return (unsigned)f2bf(a) | ((unsigned)f2bf(b) << 16); }
; __device__ __forceinline__ void scan_phase(KP P, int l) {
;     ...
; #pragma unroll
;       for (int i = 0; i < 16; ++i) {
;         uint2 o; o.x = pack2(hc0, hc1); o.y = pack2(hc2, hc3);
;         *(uint2*)(base + (long)(c0 + i) * 32 * 8192) = o;
;         hc0 = hc0 * d[i] + __uint_as_float(sv[i].x << 16); hc1 = hc1 * d[i] + __uint_as_float(sv[i].x & 0xffff0000u);
;         hc2 = hc2 * d[i] + __uint_as_float(sv[i].y << 16); hc3 = hc3 * d[i] + __uint_as_float(sv[i].y & 0xffff0000u);
	v_lshlrev_b32_e32 v61, 16, v83
	v_lshlrev_b32_e32 v60, 16, v82
	v_or_b32_sdwa v74, v11, v27 dst_sel:DWORD dst_unused:UNUSED_PAD src0_sel:WORD_1 src1_sel:DWORD
	v_add3_u32 v27, v16, v65, s33
	v_and_b32_sdwa v65, v58, v226 dst_sel:DWORD dst_unused:UNUSED_PAD src0_sel:WORD_1 src1_sel:DWORD
	v_and_b32_sdwa v39, v19, v226 dst_sel:DWORD dst_unused:UNUSED_PAD src0_sel:WORD_1 src1_sel:DWORD
	v_and_b32_sdwa v41, v18, v226 dst_sel:DWORD dst_unused:UNUSED_PAD src0_sel:WORD_1 src1_sel:DWORD
	v_and_b32_e32 v63, 0xffff0000, v83
	v_and_b32_e32 v62, 0xffff0000, v82
	v_or_b32_sdwa v75, v1, v25 dst_sel:DWORD dst_unused:UNUSED_PAD src0_sel:WORD_1 src1_sel:DWORD
	v_add3_u32 v25, v17, v49, s33
	v_pk_fma_f32 v[16:17], v[64:65], v[52:53], v[60:61] op_sel_hi:[0,1,1]
	v_add3_u32 v1, v18, v41, s33
	v_add3_u32 v11, v19, v39, s33
	v_and_b32_sdwa v49, v59, v226 dst_sel:DWORD dst_unused:UNUSED_PAD src0_sel:WORD_1 src1_sel:DWORD
	v_pk_fma_f32 v[18:19], v[64:65], v[58:59], v[62:63] op_sel_hi:[0,1,1]
	s_waitcnt vmcnt(11)
	v_and_b32_e32 v63, 0xffff0000, v85
	v_and_b32_e32 v62, 0xffff0000, v84
	v_and_b32_sdwa v67, v16, v226 dst_sel:DWORD dst_unused:UNUSED_PAD src0_sel:WORD_1 src1_sel:DWORD
	v_and_b32_sdwa v39, v53, v226 dst_sel:DWORD dst_unused:UNUSED_PAD src0_sel:WORD_1 src1_sel:DWORD
	v_and_b32_sdwa v41, v52, v226 dst_sel:DWORD dst_unused:UNUSED_PAD src0_sel:WORD_1 src1_sel:DWORD
	v_lshlrev_b32_e32 v61, 16, v85
	v_lshlrev_b32_e32 v60, 16, v84
	global_store_dwordx2 v[54:55], v[74:75], off sc1
	v_and_b32_e32 v27, 0xffff0000, v27
	v_add3_u32 v49, v59, v49, s33
	v_and_b32_sdwa v69, v19, v226 dst_sel:DWORD dst_unused:UNUSED_PAD src0_sel:WORD_1 src1_sel:DWORD
	v_pk_fma_f32 v[54:55], v[66:67], v[18:19], v[62:63] op_sel_hi:[0,1,1]
	v_and_b32_e32 v25, 0xffff0000, v25
	v_add3_u32 v41, v52, v41, s33
	v_add3_u32 v39, v53, v39, s33
	v_add3_u32 v64, v58, v65, s33
	v_and_b32_sdwa v65, v17, v226 dst_sel:DWORD dst_unused:UNUSED_PAD src0_sel:WORD_1 src1_sel:DWORD
	v_and_b32_sdwa v71, v18, v226 dst_sel:DWORD dst_unused:UNUSED_PAD src0_sel:WORD_1 src1_sel:DWORD
	v_pk_fma_f32 v[52:53], v[66:67], v[16:17], v[60:61] op_sel_hi:[0,1,1]
	s_waitcnt vmcnt(11)
	v_lshlrev_b32_e32 v59, 16, v89
	v_lshlrev_b32_e32 v58, 16, v88
	v_and_b32_e32 v61, 0xffff0000, v89
	v_and_b32_e32 v60, 0xffff0000, v88
	v_or_b32_sdwa v62, v1, v27 dst_sel:DWORD dst_unused:UNUSED_PAD src0_sel:WORD_1 src1_sel:DWORD
	v_and_b32_e32 v1, 0xffff0000, v49
	v_add3_u32 v49, v19, v69, s33
	v_and_b32_sdwa v69, v54, v226 dst_sel:DWORD dst_unused:UNUSED_PAD src0_sel:WORD_1 src1_sel:DWORD
	v_or_b32_sdwa v63, v11, v25 dst_sel:DWORD dst_unused:UNUSED_PAD src0_sel:WORD_1 src1_sel:DWORD
	v_and_b32_e32 v11, 0xffff0000, v64
	v_add3_u32 v25, v16, v67, s33
	v_add3_u32 v27, v17, v65, s33
	v_add3_u32 v64, v18, v71, s33
	v_and_b32_sdwa v65, v53, v226 dst_sel:DWORD dst_unused:UNUSED_PAD src0_sel:WORD_1 src1_sel:DWORD
	v_and_b32_sdwa v66, v52, v226 dst_sel:DWORD dst_unused:UNUSED_PAD src0_sel:WORD_1 src1_sel:DWORD
	v_and_b32_sdwa v67, v55, v226 dst_sel:DWORD dst_unused:UNUSED_PAD src0_sel:WORD_1 src1_sel:DWORD
	v_pk_fma_f32 v[16:17], v[68:69], v[52:53], v[58:59] op_sel_hi:[0,1,1]
	v_pk_fma_f32 v[18:19], v[68:69], v[54:55], v[60:61] op_sel_hi:[0,1,1]
	s_waitcnt vmcnt(10)
	v_lshlrev_b32_e32 v59, 16, v91
	v_lshlrev_b32_e32 v58, 16, v90
	v_and_b32_e32 v61, 0xffff0000, v91
	v_and_b32_e32 v60, 0xffff0000, v90
	global_store_dwordx2 v[56:57], v[62:63], off sc1
	v_or_b32_sdwa v57, v39, v1 dst_sel:DWORD dst_unused:UNUSED_PAD src0_sel:WORD_1 src1_sel:DWORD
	v_or_b32_sdwa v56, v41, v11 dst_sel:DWORD dst_unused:UNUSED_PAD src0_sel:WORD_1 src1_sel:DWORD
	v_and_b32_e32 v1, 0xffff0000, v49
	v_and_b32_e32 v11, 0xffff0000, v64
	v_add3_u32 v39, v52, v66, s33
	v_add3_u32 v41, v53, v65, s33
	v_add3_u32 v49, v55, v67, s33
	v_add3_u32 v62, v54, v69, s33
	v_and_b32_sdwa v63, v17, v226 dst_sel:DWORD dst_unused:UNUSED_PAD src0_sel:WORD_1 src1_sel:DWORD
	v_and_b32_sdwa v64, v16, v226 dst_sel:DWORD dst_unused:UNUSED_PAD src0_sel:WORD_1 src1_sel:DWORD
	v_and_b32_sdwa v65, v19, v226 dst_sel:DWORD dst_unused:UNUSED_PAD src0_sel:WORD_1 src1_sel:DWORD
	v_and_b32_sdwa v66, v18, v226 dst_sel:DWORD dst_unused:UNUSED_PAD src0_sel:WORD_1 src1_sel:DWORD
	v_pk_fma_f32 v[52:53], v[70:71], v[16:17], v[58:59] op_sel_hi:[0,1,1]
	v_pk_fma_f32 v[54:55], v[70:71], v[18:19], v[60:61] op_sel_hi:[0,1,1]
	s_waitcnt vmcnt(10)
	v_lshlrev_b32_e32 v59, 16, v93
	v_lshlrev_b32_e32 v58, 16, v92
	v_and_b32_e32 v61, 0xffff0000, v93
	v_and_b32_e32 v60, 0xffff0000, v92
	global_store_dwordx2 v[72:73], v[56:57], off sc1
	v_or_b32_sdwa v57, v27, v1 dst_sel:DWORD dst_unused:UNUSED_PAD src0_sel:WORD_1 src1_sel:DWORD
	v_or_b32_sdwa v56, v25, v11 dst_sel:DWORD dst_unused:UNUSED_PAD src0_sel:WORD_1 src1_sel:DWORD
	v_and_b32_e32 v1, 0xffff0000, v49
	v_and_b32_e32 v11, 0xffff0000, v62
	v_add3_u32 v25, v16, v64, s33
	v_add3_u32 v27, v17, v63, s33
	v_add3_u32 v62, v19, v65, s33
	v_add3_u32 v63, v18, v66, s33
	v_and_b32_sdwa v64, v53, v226 dst_sel:DWORD dst_unused:UNUSED_PAD src0_sel:WORD_1 src1_sel:DWORD
	v_and_b32_sdwa v65, v52, v226 dst_sel:DWORD dst_unused:UNUSED_PAD src0_sel:WORD_1 src1_sel:DWORD
	v_and_b32_sdwa v66, v55, v226 dst_sel:DWORD dst_unused:UNUSED_PAD src0_sel:WORD_1 src1_sel:DWORD
	v_and_b32_sdwa v67, v54, v226 dst_sel:DWORD dst_unused:UNUSED_PAD src0_sel:WORD_1 src1_sel:DWORD
	v_pk_fma_f32 v[16:17], v[48:49], v[52:53], v[58:59] op_sel_hi:[0,1,1]
	v_pk_fma_f32 v[18:19], v[48:49], v[54:55], v[60:61] op_sel_hi:[0,1,1]
	s_waitcnt vmcnt(10)
; __device__ __forceinline__ unsigned pack2(float a, float b) { return (unsigned)f2bf(a) | ((unsigned)f2bf(b) << 16); }
; __device__ __forceinline__ void scan_phase(KP P, int l) {
;     ...
; #pragma unroll
;       for (int i = 0; i < 16; ++i) {
;         uint2 o; o.x = pack2(hc0, hc1); o.y = pack2(hc2, hc3);
;         *(uint2*)(base + (long)(c0 + i) * 32 * 8192) = o;
;         hc0 = hc0 * d[i] + __uint_as_float(sv[i].x << 16); hc1 = hc1 * d[i] + __uint_as_float(sv[i].x & 0xffff0000u);
;         hc2 = hc2 * d[i] + __uint_as_float(sv[i].y << 16); hc3 = hc3 * d[i] + __uint_as_float(sv[i].y & 0xffff0000u);
	v_lshlrev_b32_e32 v49, 16, v95
	v_lshlrev_b32_e32 v48, 16, v94
	v_and_b32_e32 v59, 0xffff0000, v95
	v_and_b32_e32 v58, 0xffff0000, v94
	global_store_dwordx2 v[78:79], v[56:57], off sc1
	v_or_b32_sdwa v57, v41, v1 dst_sel:DWORD dst_unused:UNUSED_PAD src0_sel:WORD_1 src1_sel:DWORD
	v_or_b32_sdwa v56, v39, v11 dst_sel:DWORD dst_unused:UNUSED_PAD src0_sel:WORD_1 src1_sel:DWORD
	v_and_b32_e32 v1, 0xffff0000, v62
	v_and_b32_e32 v11, 0xffff0000, v63
	v_add3_u32 v60, v52, v65, s33
	v_add3_u32 v61, v53, v64, s33
	v_add3_u32 v39, v55, v66, s33
	v_add3_u32 v62, v54, v67, s33
	v_and_b32_sdwa v63, v17, v226 dst_sel:DWORD dst_unused:UNUSED_PAD src0_sel:WORD_1 src1_sel:DWORD
	v_and_b32_sdwa v64, v16, v226 dst_sel:DWORD dst_unused:UNUSED_PAD src0_sel:WORD_1 src1_sel:DWORD
	v_and_b32_sdwa v65, v19, v226 dst_sel:DWORD dst_unused:UNUSED_PAD src0_sel:WORD_1 src1_sel:DWORD
	v_and_b32_sdwa v66, v18, v226 dst_sel:DWORD dst_unused:UNUSED_PAD src0_sel:WORD_1 src1_sel:DWORD
	v_pk_fma_f32 v[48:49], v[40:41], v[16:17], v[48:49] op_sel_hi:[0,1,1]
	s_waitcnt vmcnt(10)
	v_lshlrev_b32_e32 v53, 16, v97
	v_lshlrev_b32_e32 v52, 16, v96
	v_pk_fma_f32 v[40:41], v[40:41], v[18:19], v[58:59] op_sel_hi:[0,1,1]
	v_and_b32_e32 v55, 0xffff0000, v97
	v_and_b32_e32 v54, 0xffff0000, v96
	global_store_dwordx2 v[80:81], v[56:57], off sc1
	v_or_b32_sdwa v57, v27, v1 dst_sel:DWORD dst_unused:UNUSED_PAD src0_sel:WORD_1 src1_sel:DWORD
	v_or_b32_sdwa v56, v25, v11 dst_sel:DWORD dst_unused:UNUSED_PAD src0_sel:WORD_1 src1_sel:DWORD
	v_and_b32_e32 v1, 0xffff0000, v39
	v_and_b32_e32 v11, 0xffff0000, v62
	v_add3_u32 v25, v16, v64, s33
	v_add3_u32 v27, v17, v63, s33
	v_add3_u32 v58, v19, v65, s33
	v_add3_u32 v59, v18, v66, s33
	v_and_b32_sdwa v62, v49, v226 dst_sel:DWORD dst_unused:UNUSED_PAD src0_sel:WORD_1 src1_sel:DWORD
	v_pk_fma_f32 v[16:17], v[38:39], v[48:49], v[52:53] op_sel_hi:[0,1,1]
	v_and_b32_sdwa v63, v48, v226 dst_sel:DWORD dst_unused:UNUSED_PAD src0_sel:WORD_1 src1_sel:DWORD
	v_and_b32_sdwa v64, v41, v226 dst_sel:DWORD dst_unused:UNUSED_PAD src0_sel:WORD_1 src1_sel:DWORD
	v_and_b32_sdwa v65, v40, v226 dst_sel:DWORD dst_unused:UNUSED_PAD src0_sel:WORD_1 src1_sel:DWORD
	v_pk_fma_f32 v[18:19], v[38:39], v[40:41], v[54:55] op_sel_hi:[0,1,1]
	v_or_b32_sdwa v55, v61, v1 dst_sel:DWORD dst_unused:UNUSED_PAD src0_sel:WORD_1 src1_sel:DWORD
	v_or_b32_sdwa v54, v60, v11 dst_sel:DWORD dst_unused:UNUSED_PAD src0_sel:WORD_1 src1_sel:DWORD
	v_and_b32_e32 v1, 0xffff0000, v58
	v_and_b32_e32 v11, 0xffff0000, v59
	v_add3_u32 v59, v49, v62, s33
	v_and_b32_sdwa v62, v17, v226 dst_sel:DWORD dst_unused:UNUSED_PAD src0_sel:WORD_1 src1_sel:DWORD
	s_waitcnt vmcnt(10)
	v_lshlrev_b32_e32 v38, 16, v98
	v_and_b32_e32 v39, 0xffff0000, v98
	v_add3_u32 v58, v48, v63, s33
	v_add3_u32 v60, v41, v64, s33
	v_add3_u32 v61, v40, v65, s33
	v_and_b32_sdwa v63, v16, v226 dst_sel:DWORD dst_unused:UNUSED_PAD src0_sel:WORD_1 src1_sel:DWORD
	v_and_b32_sdwa v64, v19, v226 dst_sel:DWORD dst_unused:UNUSED_PAD src0_sel:WORD_1 src1_sel:DWORD
	v_and_b32_sdwa v65, v18, v226 dst_sel:DWORD dst_unused:UNUSED_PAD src0_sel:WORD_1 src1_sel:DWORD
	v_mov_b32_e32 v40, v16
	v_mov_b32_e32 v41, v18
	global_store_dwordx2 v[50:51], v[54:55], off sc1
	v_or_b32_sdwa v51, v27, v1 dst_sel:DWORD dst_unused:UNUSED_PAD src0_sel:WORD_1 src1_sel:DWORD
	v_add3_u32 v27, v17, v62, s33
	v_lshlrev_b32_e32 v52, 16, v99
	v_and_b32_e32 v53, 0xffff0000, v99
	s_waitcnt vmcnt(10)
	v_lshlrev_b32_e32 v48, 16, v100
	v_and_b32_e32 v49, 0xffff0000, v100
	v_or_b32_sdwa v50, v25, v11 dst_sel:DWORD dst_unused:UNUSED_PAD src0_sel:WORD_1 src1_sel:DWORD
	v_and_b32_e32 v1, 0xffff0000, v60
	v_and_b32_e32 v11, 0xffff0000, v61
	v_add3_u32 v25, v16, v63, s33
	v_add3_u32 v60, v19, v64, s33
	v_add3_u32 v61, v18, v65, s33
	v_mov_b32_e32 v18, v17
	v_pk_fma_f32 v[38:39], v[26:27], v[40:41], v[38:39] op_sel_hi:[0,1,1]
	global_store_dwordx2 v[86:87], v[56:57], off sc1
	v_lshlrev_b32_e32 v56, 16, v101
	v_and_b32_e32 v57, 0xffff0000, v101
	s_waitcnt vmcnt(10)
	v_lshlrev_b32_e32 v16, 16, v102
	v_and_b32_e32 v17, 0xffff0000, v102
	v_or_b32_sdwa v41, v59, v1 dst_sel:DWORD dst_unused:UNUSED_PAD src0_sel:WORD_1 src1_sel:DWORD
	v_or_b32_sdwa v40, v58, v11 dst_sel:DWORD dst_unused:UNUSED_PAD src0_sel:WORD_1 src1_sel:DWORD
	v_and_b32_e32 v1, 0xffff0000, v60
	v_and_b32_e32 v11, 0xffff0000, v61
	v_pk_fma_f32 v[48:49], v[24:25], v[38:39], v[48:49] op_sel_hi:[0,1,1]
	v_pk_fma_f32 v[18:19], v[26:27], v[18:19], v[52:53] op_sel_hi:[0,1,1]
	v_and_b32_sdwa v52, v38, v226 dst_sel:DWORD dst_unused:UNUSED_PAD src0_sel:WORD_1 src1_sel:DWORD
	v_and_b32_sdwa v53, v39, v226 dst_sel:DWORD dst_unused:UNUSED_PAD src0_sel:WORD_1 src1_sel:DWORD
	v_lshlrev_b32_e32 v54, 16, v103
	v_and_b32_e32 v55, 0xffff0000, v103
	global_store_dwordx2 v[46:47], v[50:51], off sc1
	s_waitcnt vmcnt(10)
	v_lshlrev_b32_e32 v46, 16, v104
	v_and_b32_e32 v47, 0xffff0000, v104
	global_store_dwordx2 v[44:45], v[40:41], off sc1
	v_or_b32_sdwa v27, v27, v1 dst_sel:DWORD dst_unused:UNUSED_PAD src0_sel:WORD_1 src1_sel:DWORD
	v_or_b32_sdwa v26, v25, v11 dst_sel:DWORD dst_unused:UNUSED_PAD src0_sel:WORD_1 src1_sel:DWORD
	s_waitcnt vmcnt(10)
; __device__ __forceinline__ unsigned pack2(float a, float b) { return (unsigned)f2bf(a) | ((unsigned)f2bf(b) << 16); }
; __device__ __forceinline__ void scan_phase(KP P, int l) {
;     ...
; #pragma unroll
;       for (int i = 0; i < 16; ++i) {
;         uint2 o; o.x = pack2(hc0, hc1); o.y = pack2(hc2, hc3);
;         *(uint2*)(base + (long)(c0 + i) * 32 * 8192) = o;
;         hc0 = hc0 * d[i] + __uint_as_float(sv[i].x << 16); hc1 = hc1 * d[i] + __uint_as_float(sv[i].x & 0xffff0000u);
;         hc2 = hc2 * d[i] + __uint_as_float(sv[i].y << 16); hc3 = hc3 * d[i] + __uint_as_float(sv[i].y & 0xffff0000u);
;       }
;     }
;     *(float4*)(P->out + O_SSMP + (long)(l * 2 + b) * 262144 + (long)rem * 4) = make_float4(hc0, hc1, hc2, hc3);
	v_lshlrev_b32_e32 v40, 16, v8
	v_and_b32_e32 v41, 0xffff0000, v8
	v_lshlrev_b32_e32 v44, 16, v9
	v_and_b32_e32 v45, 0xffff0000, v9
	v_pk_fma_f32 v[8:9], v[22:23], v[48:49], v[16:17] op_sel_hi:[0,1,1]
	v_and_b32_sdwa v1, v18, v226 dst_sel:DWORD dst_unused:UNUSED_PAD src0_sel:WORD_1 src1_sel:DWORD
	v_add3_u32 v11, v38, v52, s33
	v_and_b32_sdwa v52, v19, v226 dst_sel:DWORD dst_unused:UNUSED_PAD src0_sel:WORD_1 src1_sel:DWORD
	v_add3_u32 v53, v39, v53, s33
	v_pk_fma_f32 v[16:17], v[24:25], v[18:19], v[56:57] op_sel_hi:[0,1,1]
	v_and_b32_sdwa v56, v48, v226 dst_sel:DWORD dst_unused:UNUSED_PAD src0_sel:WORD_1 src1_sel:DWORD
	v_and_b32_sdwa v57, v49, v226 dst_sel:DWORD dst_unused:UNUSED_PAD src0_sel:WORD_1 src1_sel:DWORD
	v_lshlrev_b32_e32 v50, 16, v105
	v_and_b32_e32 v51, 0xffff0000, v105
	global_store_dwordx2 v[42:43], v[26:27], off sc1
	v_pk_fma_f32 v[26:27], v[20:21], v[8:9], v[46:47] op_sel_hi:[0,1,1]
	v_add3_u32 v1, v18, v1, s33
	v_add3_u32 v42, v19, v52, s33
	v_and_b32_e32 v43, 0xffff0000, v53
	v_and_b32_sdwa v46, v16, v226 dst_sel:DWORD dst_unused:UNUSED_PAD src0_sel:WORD_1 src1_sel:DWORD
	v_add3_u32 v47, v48, v56, s33
	v_and_b32_sdwa v48, v17, v226 dst_sel:DWORD dst_unused:UNUSED_PAD src0_sel:WORD_1 src1_sel:DWORD
	v_add3_u32 v49, v49, v57, s33
	v_pk_fma_f32 v[18:19], v[22:23], v[16:17], v[54:55] op_sel_hi:[0,1,1]
	v_and_b32_sdwa v52, v9, v226 dst_sel:DWORD dst_unused:UNUSED_PAD src0_sel:WORD_1 src1_sel:DWORD
	s_waitcnt vmcnt(10)
	v_lshlrev_b32_e32 v24, 16, v106
	v_and_b32_e32 v25, 0xffff0000, v106
	v_and_b32_sdwa v22, v8, v226 dst_sel:DWORD dst_unused:UNUSED_PAD src0_sel:WORD_1 src1_sel:DWORD
	v_pk_fma_f32 v[40:41], v[10:11], v[26:27], v[40:41] op_sel_hi:[0,1,1]
	v_and_b32_e32 v53, 0xffff0000, v42
	v_or_b32_sdwa v42, v11, v43 dst_sel:DWORD dst_unused:UNUSED_PAD src0_sel:WORD_1 src1_sel:DWORD
	v_add3_u32 v11, v16, v46, s33
	v_add3_u32 v46, v17, v48, s33
	v_and_b32_e32 v48, 0xffff0000, v49
	v_and_b32_sdwa v49, v18, v226 dst_sel:DWORD dst_unused:UNUSED_PAD src0_sel:WORD_1 src1_sel:DWORD
	v_and_b32_sdwa v54, v19, v226 dst_sel:DWORD dst_unused:UNUSED_PAD src0_sel:WORD_1 src1_sel:DWORD
	v_add3_u32 v52, v9, v52, s33
	v_pk_fma_f32 v[16:17], v[20:21], v[18:19], v[50:51] op_sel_hi:[0,1,1]
	v_and_b32_sdwa v20, v26, v226 dst_sel:DWORD dst_unused:UNUSED_PAD src0_sel:WORD_1 src1_sel:DWORD
	v_and_b32_sdwa v50, v27, v226 dst_sel:DWORD dst_unused:UNUSED_PAD src0_sel:WORD_1 src1_sel:DWORD
	v_add3_u32 v22, v8, v22, s33
	v_pk_fma_f32 v[8:9], v[2:3], v[40:41], v[24:25] op_sel_hi:[0,1,1]
	v_or_b32_sdwa v43, v1, v53 dst_sel:DWORD dst_unused:UNUSED_PAD src0_sel:WORD_1 src1_sel:DWORD
	v_and_b32_e32 v1, 0xffff0000, v46
	v_or_b32_sdwa v24, v47, v48 dst_sel:DWORD dst_unused:UNUSED_PAD src0_sel:WORD_1 src1_sel:DWORD
	v_add3_u32 v46, v18, v49, s33
	v_add3_u32 v18, v19, v54, s33
	v_and_b32_e32 v19, 0xffff0000, v52
	v_add3_u32 v20, v26, v20, s33
	v_and_b32_sdwa v48, v17, v226 dst_sel:DWORD dst_unused:UNUSED_PAD src0_sel:WORD_1 src1_sel:DWORD
	v_add3_u32 v49, v27, v50, s33
	v_pk_fma_f32 v[26:27], v[10:11], v[16:17], v[44:45] op_sel_hi:[0,1,1]
	v_and_b32_sdwa v47, v16, v226 dst_sel:DWORD dst_unused:UNUSED_PAD src0_sel:WORD_1 src1_sel:DWORD
	v_and_b32_sdwa v44, v41, v226 dst_sel:DWORD dst_unused:UNUSED_PAD src0_sel:WORD_1 src1_sel:DWORD
	global_store_dwordx2 v[34:35], v[42:43], off sc1
	v_or_b32_sdwa v25, v11, v1 dst_sel:DWORD dst_unused:UNUSED_PAD src0_sel:WORD_1 src1_sel:DWORD
	v_and_b32_e32 v1, 0xffff0000, v18
	v_or_b32_sdwa v34, v22, v19 dst_sel:DWORD dst_unused:UNUSED_PAD src0_sel:WORD_1 src1_sel:DWORD
	v_add3_u32 v17, v17, v48, s33
	v_and_b32_e32 v19, 0xffff0000, v49
	v_and_b32_sdwa v43, v27, v226 dst_sel:DWORD dst_unused:UNUSED_PAD src0_sel:WORD_1 src1_sel:DWORD
	v_lshlrev_b32_e32 v38, 16, v107
	v_and_b32_e32 v39, 0xffff0000, v107
	v_and_b32_sdwa v10, v40, v226 dst_sel:DWORD dst_unused:UNUSED_PAD src0_sel:WORD_1 src1_sel:DWORD
	v_add3_u32 v22, v16, v47, s33
	v_and_b32_sdwa v42, v26, v226 dst_sel:DWORD dst_unused:UNUSED_PAD src0_sel:WORD_1 src1_sel:DWORD
	v_add3_u32 v41, v41, v44, s33
	global_store_dwordx2 v[30:31], v[24:25], off sc1
	v_or_b32_sdwa v35, v46, v1 dst_sel:DWORD dst_unused:UNUSED_PAD src0_sel:WORD_1 src1_sel:DWORD
	v_and_b32_e32 v1, 0xffff0000, v17
	v_or_b32_sdwa v24, v20, v19 dst_sel:DWORD dst_unused:UNUSED_PAD src0_sel:WORD_1 src1_sel:DWORD
	v_add3_u32 v20, v27, v43, s33
	v_add3_u32 v40, v40, v10, s33
	v_pk_fma_f32 v[10:11], v[2:3], v[26:27], v[38:39] op_sel_hi:[0,1,1]
	v_add3_u32 v2, v26, v42, s33
	v_and_b32_e32 v26, 0xffff0000, v41
	v_or_b32_sdwa v25, v22, v1 dst_sel:DWORD dst_unused:UNUSED_PAD src0_sel:WORD_1 src1_sel:DWORD
	v_and_b32_e32 v1, 0xffff0000, v20
	v_mov_b32_e32 v16, v9
	v_mov_b32_e32 v18, v8
	v_mov_b32_e32 v17, v11
	v_mov_b32_e32 v19, v10
	v_or_b32_sdwa v26, v40, v26 dst_sel:DWORD dst_unused:UNUSED_PAD src0_sel:WORD_1 src1_sel:DWORD
	v_or_b32_sdwa v27, v2, v1 dst_sel:DWORD dst_unused:UNUSED_PAD src0_sel:WORD_1 src1_sel:DWORD
	global_store_dwordx2 v[28:29], v[34:35], off sc1
	global_store_dwordx2 v[32:33], v[24:25], off sc1
	global_store_dwordx2 v[36:37], v[26:27], off sc1
	s_cbranch_scc0 .LBB0_879
	s_load_dwordx2 s[0:1], s[4:5], 0xd0
	v_add_u32_e32 v0, s47, v0
	v_ashrrev_i32_e32 v1, 31, v0
	v_lshlrev_b64 v[0:1], 20, v[0:1]
	v_lshlrev_b32_e32 v2, 4, v23
	s_waitcnt lgkmcnt(0)
	v_lshl_add_u64 v[0:1], s[0:1], 0, v[0:1]
	v_lshl_add_u64 v[0:1], v[0:1], 0, v[2:3]
	v_add_co_u32_e32 v0, vcc, 0x6500000, v0
	s_mov_b32 s0, s48
	s_nop 0
	v_addc_co_u32_e32 v1, vcc, 0, v1, vcc
	global_store_dwordx4 v[0:1], v[8:11], off sc1
	s_nop 0
	v_lshl_add_u32 v21, s0, 9, v21
	s_mov_b32 s0, 0x1ffff
	v_cmp_lt_i32_e32 vcc, s0, v21
	s_or_b64 s[10:11], vcc, s[10:11]
	s_andn2_b64 exec, exec, s[10:11]
	s_cbranch_execnz .LBB0_878
	s_or_b64 exec, exec, s[10:11]

; __device__ __forceinline__ unsigned pack2(float a, float b) { return (unsigned)f2bf(a) | ((unsigned)f2bf(b) << 16); }
; __device__ __forceinline__ void rmsnorm_phase(const float* __restrict__ xp_, const float* __restrict__ xs_, const float* __restrict__ g, u16* __restrict__ xn) {
;     ...
;   for (int r = gw; r < NRP; r += nw) {
;     u16* o = xn + (long)r * D;
;     if (r >= NR) {
; #pragma unroll
;       for (int i = 0; i < 8; ++i) *(uint2*)(o + (i * 64 + lane) * 4) = make_uint2(zz, zz);
;       continue;
;     }
;     const float* x = (r < NP) ? xp_ + (long)r * D : xs_ + (long)(r - NP) * D;
;     float4 v[8]; float ss = 0.f;
; #pragma unroll
;     for (int i = 0; i < 8; ++i) { v[i] = ((const float4*)x)[i * 64 + lane]; ss += v[i].x * v[i].x + v[i].y * v[i].y + v[i].z * v[i].z + v[i].w * v[i].w; }
;     ss = wave_sum(ss, lane);
;     const float rstd = rsqrtf(ss * (1.f / 2048.f) + EPS);
; #pragma unroll
;     for (int i = 0; i < 8; ++i) {
;       const float4 gg = gg8[i];
;       uint2 pk; pk.x = pack2(v[i].x * rstd * gg.x, v[i].y * rstd * gg.y); pk.y = pack2(v[i].z * rstd * gg.z, v[i].w * rstd * gg.w);
;       *(uint2*)(o + (i * 64 + lane) * 4) = pk;
;     }
;   }
.LBB0_1200:
	s_or_b64 exec, exec, s[0:1]
	v_add_u32_e32 v60, s8, v60
	s_movk_i32 s0, 0x20ff
	v_cmp_lt_i32_e32 vcc, s0, v60
	global_store_dwordx2 v[70:71], v[38:39], off offset:1536 sc1
	v_lshl_add_u64 v[72:73], v[72:73], 0, s[12:13]
	s_or_b64 s[10:11], vcc, s[10:11]
	v_lshl_add_u64 v[70:71], v[70:71], 0, s[14:15]
	s_andn2_b64 exec, exec, s[10:11]
	s_cbranch_execz .LBB0_1205
.LBB0_1201:
	s_movk_i32 s0, 0x2080
	v_cmp_gt_i32_e32 vcc, s0, v60
	s_and_saveexec_b64 s[0:1], vcc
	s_xor_b64 s[20:21], exec, s[0:1]
	s_cbranch_execz .LBB0_1203
	v_add_u32_e32 v2, 0xffffe000, v60
	s_movk_i32 s0, 0x2000
	v_lshlrev_b64 v[38:39], 13, v[2:3]
	v_cmp_gt_i32_e32 vcc, s0, v60
	v_lshl_add_u64 v[38:39], s[6:7], 0, v[38:39]
	v_mov_b32_e32 v63, v3
	v_cndmask_b32_e32 v39, v39, v73, vcc
	v_cndmask_b32_e32 v38, v38, v72, vcc
	v_mov_b32_e32 v65, v3
	v_mov_b32_e32 v67, v3
	v_mov_b32_e32 v69, v3
	v_mov_b32_e32 v77, v3
	v_lshl_add_u64 v[42:43], v[38:39], 0, v[62:63]
	v_lshl_add_u64 v[46:47], v[38:39], 0, v[64:65]
	v_lshl_add_u64 v[82:83], v[38:39], 0, v[66:67]
	v_lshl_add_u64 v[52:53], v[38:39], 0, v[68:69]
	v_lshl_add_u64 v[38:39], v[38:39], 0, v[76:77]
	global_load_dwordx4 v[38:41], v[38:39], off
	s_nop 0
	global_load_dwordx4 v[56:59], v[42:43], off
	global_load_dwordx4 v[48:51], v[42:43], off offset:2048
	global_load_dwordx4 v[90:93], v[46:47], off
	s_waitcnt vmcnt(2)
	v_mul_f32_e32 v2, v57, v57
	v_fmac_f32_e32 v2, v56, v56
	v_fmac_f32_e32 v2, v58, v58
	v_mov_b32_e32 v88, v56
	v_mov_b32_e32 v89, v58
	v_mov_b32_e32 v58, v57
	global_load_dwordx4 v[54:57], v[42:43], off offset:1024
	v_fmac_f32_e32 v2, v59, v59
	s_waitcnt vmcnt(2)
	v_mov_b32_e32 v84, v48
	v_mov_b32_e32 v85, v50
	s_waitcnt vmcnt(1)
	v_mov_b32_e32 v80, v90
	v_mov_b32_e32 v81, v92
	s_waitcnt vmcnt(0)
	v_mul_f32_e32 v44, v55, v55
	v_fmac_f32_e32 v44, v54, v54
	v_fmac_f32_e32 v44, v56, v56
	v_fmac_f32_e32 v44, v57, v57
	v_add_f32_e32 v2, v2, v44
	v_mul_f32_e32 v44, v49, v49
	v_fmac_f32_e32 v44, v48, v48
	v_fmac_f32_e32 v44, v50, v50
	v_fmac_f32_e32 v44, v51, v51
	v_add_f32_e32 v2, v2, v44
	global_load_dwordx4 v[42:45], v[42:43], off offset:3072
	v_mov_b32_e32 v50, v49
	v_mov_b32_e32 v86, v54
	v_mov_b32_e32 v87, v56
	v_mov_b32_e32 v56, v55
	v_mov_b32_e32 v54, v90
	s_waitcnt vmcnt(0)
	v_mul_f32_e32 v48, v43, v43
	v_fmac_f32_e32 v48, v42, v42
	v_fmac_f32_e32 v48, v44, v44
	v_fmac_f32_e32 v48, v45, v45
	v_add_f32_e32 v2, v2, v48
	global_load_dwordx4 v[46:49], v[82:83], off
	v_mov_b32_e32 v82, v91
	v_mov_b32_e32 v78, v42
	v_mov_b32_e32 v42, v91
	v_mov_b32_e32 v91, v39
	v_mov_b32_e32 v79, v44
	v_mov_b32_e32 v44, v43
	v_mov_b32_e32 v43, v93
	s_waitcnt vmcnt(0)
	v_mov_b32_e32 v83, v47
	v_mov_b32_e32 v55, v46
	v_pk_mul_f32 v[82:83], v[82:83], v[82:83]
	s_nop 0
	v_pk_fma_f32 v[54:55], v[54:55], v[54:55], v[82:83]
	v_mov_b32_e32 v82, v92
	v_mov_b32_e32 v83, v48
	v_pk_fma_f32 v[54:55], v[82:83], v[82:83], v[54:55]
	v_mov_b32_e32 v82, v93
	v_mov_b32_e32 v83, v49
	v_pk_fma_f32 v[54:55], v[82:83], v[82:83], v[54:55]
	v_mov_b32_e32 v82, v46
	v_add_f32_e32 v2, v2, v54
	v_add_f32_e32 v2, v2, v55
	global_load_dwordx4 v[52:55], v[52:53], off
	v_mov_b32_e32 v83, v48
	v_mov_b32_e32 v48, v47
	v_mov_b32_e32 v47, v38
	s_waitcnt vmcnt(0)
	v_mov_b32_e32 v90, v53
	v_mov_b32_e32 v46, v52
	v_pk_mul_f32 v[90:91], v[90:91], v[90:91]
	s_nop 0
	v_pk_fma_f32 v[46:47], v[46:47], v[46:47], v[90:91]
	v_mov_b32_e32 v90, v54
	v_mov_b32_e32 v91, v40
	v_pk_fma_f32 v[46:47], v[90:91], v[90:91], v[46:47]
	v_mov_b32_e32 v90, v55
	v_mov_b32_e32 v91, v41
	v_pk_fma_f32 v[46:47], v[90:91], v[90:91], v[46:47]
	s_nop 0
	v_add_f32_e32 v2, v2, v46
	v_add_f32_e32 v2, v2, v47
	ds_swizzle_b32 v46, v2 offset:swizzle(SWAP,1)
	s_waitcnt lgkmcnt(0)
	v_add_f32_e32 v2, v2, v46
	ds_swizzle_b32 v46, v2 offset:swizzle(SWAP,2)
	s_waitcnt lgkmcnt(0)
	v_add_f32_e32 v2, v2, v46
	ds_swizzle_b32 v46, v2 offset:swizzle(SWAP,4)
	s_waitcnt lgkmcnt(0)
	v_add_f32_e32 v2, v2, v46
	ds_swizzle_b32 v46, v2 offset:swizzle(SWAP,8)
	s_waitcnt lgkmcnt(0)
	v_add_f32_e32 v2, v2, v46
	ds_swizzle_b32 v46, v2 offset:swizzle(SWAP,16)
	s_waitcnt lgkmcnt(0)
	v_add_f32_e32 v2, v2, v46
	ds_bpermute_b32 v46, v61, v2
	s_waitcnt lgkmcnt(0)
	v_add_f32_e32 v2, v2, v46
	v_fmamk_f32 v2, v2, 0x3a000000, v189
	v_cmp_gt_f32_e32 vcc, s62, v2
	v_mul_f32_e32 v46, 0x4b800000, v2
	s_nop 0
	v_cndmask_b32_e32 v2, v2, v46, vcc
	v_rsq_f32_e32 v2, v2
	s_nop 0
	v_mul_f32_e32 v46, 0x45800000, v2
	v_cndmask_b32_e32 v2, v2, v46, vcc
	v_pk_mul_f32 v[46:47], v[88:89], v[2:3] op_sel_hi:[1,0]
	v_pk_mul_f32 v[58:59], v[58:59], v[2:3] op_sel_hi:[1,0]
	v_pk_mul_f32 v[46:47], v[12:13], v[46:47]
	v_pk_mul_f32 v[58:59], v[10:11], v[58:59]
	v_and_b32_sdwa v63, v47, v226 dst_sel:DWORD dst_unused:UNUSED_PAD src0_sel:WORD_1 src1_sel:DWORD
	v_and_b32_sdwa v65, v46, v226 dst_sel:DWORD dst_unused:UNUSED_PAD src0_sel:WORD_1 src1_sel:DWORD
	v_add3_u32 v46, v46, v65, s33
	v_add3_u32 v47, v47, v63, s33
	v_and_b32_sdwa v63, v59, v226 dst_sel:DWORD dst_unused:UNUSED_PAD src0_sel:WORD_1 src1_sel:DWORD
	v_and_b32_sdwa v65, v58, v226 dst_sel:DWORD dst_unused:UNUSED_PAD src0_sel:WORD_1 src1_sel:DWORD
	v_add3_u32 v59, v59, v63, s33
	v_add3_u32 v58, v58, v65, s33
	v_and_b32_e32 v59, 0xffff0000, v59
	v_and_b32_e32 v58, 0xffff0000, v58
	v_or_b32_sdwa v47, v59, v47 dst_sel:DWORD dst_unused:UNUSED_PAD src0_sel:DWORD src1_sel:WORD_1
	v_or_b32_sdwa v46, v58, v46 dst_sel:DWORD dst_unused:UNUSED_PAD src0_sel:DWORD src1_sel:WORD_1
	global_store_dwordx2 v[70:71], v[46:47], off offset:-2048 sc1
	v_pk_mul_f32 v[46:47], v[86:87], v[2:3] op_sel_hi:[1,0]
	v_pk_mul_f32 v[56:57], v[56:57], v[2:3] op_sel_hi:[1,0]
	v_pk_mul_f32 v[46:47], v[16:17], v[46:47]
; __device__ __forceinline__ unsigned pack2(float a, float b) { return (unsigned)f2bf(a) | ((unsigned)f2bf(b) << 16); }
; __device__ __forceinline__ void rmsnorm_phase(const float* __restrict__ xp_, const float* __restrict__ xs_, const float* __restrict__ g, u16* __restrict__ xn) {
;     ...
; #pragma unroll
;     for (int i = 0; i < 8; ++i) {
;       const float4 gg = gg8[i];
;       uint2 pk; pk.x = pack2(v[i].x * rstd * gg.x, v[i].y * rstd * gg.y); pk.y = pack2(v[i].z * rstd * gg.z, v[i].w * rstd * gg.w);
;       *(uint2*)(o + (i * 64 + lane) * 4) = pk;
;     }
	v_pk_mul_f32 v[56:57], v[14:15], v[56:57]
	v_and_b32_sdwa v58, v47, v226 dst_sel:DWORD dst_unused:UNUSED_PAD src0_sel:WORD_1 src1_sel:DWORD
	v_and_b32_sdwa v59, v46, v226 dst_sel:DWORD dst_unused:UNUSED_PAD src0_sel:WORD_1 src1_sel:DWORD
	v_add3_u32 v46, v46, v59, s33
	v_add3_u32 v47, v47, v58, s33
	v_and_b32_sdwa v58, v57, v226 dst_sel:DWORD dst_unused:UNUSED_PAD src0_sel:WORD_1 src1_sel:DWORD
	v_and_b32_sdwa v59, v56, v226 dst_sel:DWORD dst_unused:UNUSED_PAD src0_sel:WORD_1 src1_sel:DWORD
	v_add3_u32 v57, v57, v58, s33
	v_add3_u32 v56, v56, v59, s33
	v_and_b32_e32 v57, 0xffff0000, v57
	v_and_b32_e32 v56, 0xffff0000, v56
	v_or_b32_sdwa v47, v57, v47 dst_sel:DWORD dst_unused:UNUSED_PAD src0_sel:DWORD src1_sel:WORD_1
	v_or_b32_sdwa v46, v56, v46 dst_sel:DWORD dst_unused:UNUSED_PAD src0_sel:DWORD src1_sel:WORD_1
	global_store_dwordx2 v[70:71], v[46:47], off offset:-1536 sc1
	v_pk_mul_f32 v[46:47], v[84:85], v[2:3] op_sel_hi:[1,0]
	v_pk_mul_f32 v[50:51], v[50:51], v[2:3] op_sel_hi:[1,0]
	v_pk_mul_f32 v[46:47], v[20:21], v[46:47]
	v_pk_mul_f32 v[50:51], v[18:19], v[50:51]
	v_and_b32_sdwa v56, v47, v226 dst_sel:DWORD dst_unused:UNUSED_PAD src0_sel:WORD_1 src1_sel:DWORD
	v_and_b32_sdwa v57, v46, v226 dst_sel:DWORD dst_unused:UNUSED_PAD src0_sel:WORD_1 src1_sel:DWORD
	v_add3_u32 v46, v46, v57, s33
	v_add3_u32 v47, v47, v56, s33
	v_and_b32_sdwa v56, v51, v226 dst_sel:DWORD dst_unused:UNUSED_PAD src0_sel:WORD_1 src1_sel:DWORD
	v_and_b32_sdwa v57, v50, v226 dst_sel:DWORD dst_unused:UNUSED_PAD src0_sel:WORD_1 src1_sel:DWORD
	v_add3_u32 v51, v51, v56, s33
	v_add3_u32 v50, v50, v57, s33
	v_and_b32_e32 v51, 0xffff0000, v51
	v_and_b32_e32 v50, 0xffff0000, v50
	v_or_b32_sdwa v47, v51, v47 dst_sel:DWORD dst_unused:UNUSED_PAD src0_sel:DWORD src1_sel:WORD_1
	v_or_b32_sdwa v46, v50, v46 dst_sel:DWORD dst_unused:UNUSED_PAD src0_sel:DWORD src1_sel:WORD_1
	global_store_dwordx2 v[70:71], v[46:47], off offset:-1024 sc1
	v_pk_mul_f32 v[46:47], v[78:79], v[2:3] op_sel_hi:[1,0]
	v_pk_mul_f32 v[44:45], v[44:45], v[2:3] op_sel_hi:[1,0]
	v_pk_mul_f32 v[46:47], v[24:25], v[46:47]
	v_pk_mul_f32 v[44:45], v[22:23], v[44:45]
	v_and_b32_sdwa v50, v47, v226 dst_sel:DWORD dst_unused:UNUSED_PAD src0_sel:WORD_1 src1_sel:DWORD
	v_and_b32_sdwa v51, v46, v226 dst_sel:DWORD dst_unused:UNUSED_PAD src0_sel:WORD_1 src1_sel:DWORD
	v_add3_u32 v46, v46, v51, s33
	v_add3_u32 v47, v47, v50, s33
	v_and_b32_sdwa v50, v45, v226 dst_sel:DWORD dst_unused:UNUSED_PAD src0_sel:WORD_1 src1_sel:DWORD
	v_and_b32_sdwa v51, v44, v226 dst_sel:DWORD dst_unused:UNUSED_PAD src0_sel:WORD_1 src1_sel:DWORD
	v_add3_u32 v45, v45, v50, s33
	v_add3_u32 v44, v44, v51, s33
	v_and_b32_e32 v45, 0xffff0000, v45
	v_and_b32_e32 v44, 0xffff0000, v44
	v_or_b32_sdwa v45, v45, v47 dst_sel:DWORD dst_unused:UNUSED_PAD src0_sel:DWORD src1_sel:WORD_1
	v_or_b32_sdwa v44, v44, v46 dst_sel:DWORD dst_unused:UNUSED_PAD src0_sel:DWORD src1_sel:WORD_1
	global_store_dwordx2 v[70:71], v[44:45], off offset:-512 sc1
	v_pk_mul_f32 v[44:45], v[80:81], v[2:3] op_sel_hi:[1,0]
	v_pk_mul_f32 v[42:43], v[42:43], v[2:3] op_sel_hi:[1,0]
	v_pk_mul_f32 v[44:45], v[28:29], v[44:45]
	v_pk_mul_f32 v[42:43], v[26:27], v[42:43]
	v_and_b32_sdwa v46, v45, v226 dst_sel:DWORD dst_unused:UNUSED_PAD src0_sel:WORD_1 src1_sel:DWORD
	v_and_b32_sdwa v47, v44, v226 dst_sel:DWORD dst_unused:UNUSED_PAD src0_sel:WORD_1 src1_sel:DWORD
	v_add3_u32 v44, v44, v47, s33
	v_add3_u32 v45, v45, v46, s33
	v_and_b32_sdwa v46, v43, v226 dst_sel:DWORD dst_unused:UNUSED_PAD src0_sel:WORD_1 src1_sel:DWORD
	v_and_b32_sdwa v47, v42, v226 dst_sel:DWORD dst_unused:UNUSED_PAD src0_sel:WORD_1 src1_sel:DWORD
	v_add3_u32 v43, v43, v46, s33
	v_add3_u32 v42, v42, v47, s33
	v_and_b32_e32 v43, 0xffff0000, v43
	v_and_b32_e32 v42, 0xffff0000, v42
	v_or_b32_sdwa v43, v43, v45 dst_sel:DWORD dst_unused:UNUSED_PAD src0_sel:DWORD src1_sel:WORD_1
; __device__ __forceinline__ unsigned pack2(float a, float b) { return (unsigned)f2bf(a) | ((unsigned)f2bf(b) << 16); }
; __device__ __forceinline__ void rmsnorm_phase(const float* __restrict__ xp_, const float* __restrict__ xs_, const float* __restrict__ g, u16* __restrict__ xn) {
;     ...
;     if (r >= NR) {
; #pragma unroll
;       for (int i = 0; i < 8; ++i) *(uint2*)(o + (i * 64 + lane) * 4) = make_uint2(zz, zz);
;       continue;
;     }
;     const float* x = (r < NP) ? xp_ + (long)r * D : xs_ + (long)(r - NP) * D;
;     float4 v[8]; float ss = 0.f;
; #pragma unroll
;     for (int i = 0; i < 8; ++i) { v[i] = ((const float4*)x)[i * 64 + lane]; ss += v[i].x * v[i].x + v[i].y * v[i].y + v[i].z * v[i].z + v[i].w * v[i].w; }
;     ss = wave_sum(ss, lane);
;     const float rstd = rsqrtf(ss * (1.f / 2048.f) + EPS);
; #pragma unroll
;     for (int i = 0; i < 8; ++i) {
;       const float4 gg = gg8[i];
;       uint2 pk; pk.x = pack2(v[i].x * rstd * gg.x, v[i].y * rstd * gg.y); pk.y = pack2(v[i].z * rstd * gg.z, v[i].w * rstd * gg.w);
;       *(uint2*)(o + (i * 64 + lane) * 4) = pk;
;     }
	v_or_b32_sdwa v42, v42, v44 dst_sel:DWORD dst_unused:UNUSED_PAD src0_sel:DWORD src1_sel:WORD_1
	global_store_dwordx2 v[70:71], v[42:43], off sc1
	v_pk_mul_f32 v[42:43], v[82:83], v[2:3] op_sel_hi:[1,0]
	v_pk_mul_f32 v[44:45], v[48:49], v[2:3] op_sel_hi:[1,0]
	v_pk_mul_f32 v[42:43], v[32:33], v[42:43]
	v_pk_mul_f32 v[44:45], v[30:31], v[44:45]
	v_and_b32_sdwa v46, v43, v226 dst_sel:DWORD dst_unused:UNUSED_PAD src0_sel:WORD_1 src1_sel:DWORD
	v_and_b32_sdwa v47, v42, v226 dst_sel:DWORD dst_unused:UNUSED_PAD src0_sel:WORD_1 src1_sel:DWORD
	v_add3_u32 v42, v42, v47, s33
	v_add3_u32 v43, v43, v46, s33
	v_and_b32_sdwa v46, v45, v226 dst_sel:DWORD dst_unused:UNUSED_PAD src0_sel:WORD_1 src1_sel:DWORD
	v_and_b32_sdwa v47, v44, v226 dst_sel:DWORD dst_unused:UNUSED_PAD src0_sel:WORD_1 src1_sel:DWORD
	v_add3_u32 v45, v45, v46, s33
	v_add3_u32 v44, v44, v47, s33
	v_and_b32_e32 v45, 0xffff0000, v45
	v_and_b32_e32 v44, 0xffff0000, v44
	v_or_b32_sdwa v43, v45, v43 dst_sel:DWORD dst_unused:UNUSED_PAD src0_sel:DWORD src1_sel:WORD_1
	v_or_b32_sdwa v42, v44, v42 dst_sel:DWORD dst_unused:UNUSED_PAD src0_sel:DWORD src1_sel:WORD_1
	global_store_dwordx2 v[70:71], v[42:43], off offset:512 sc1
	v_mov_b32_e32 v42, v52
	v_mov_b32_e32 v43, v54
	v_pk_mul_f32 v[42:43], v[42:43], v[2:3] op_sel_hi:[1,0]
	v_mov_b32_e32 v54, v53
	v_pk_mul_f32 v[42:43], v[36:37], v[42:43]
	v_pk_mul_f32 v[44:45], v[54:55], v[2:3] op_sel_hi:[1,0]
	v_and_b32_sdwa v46, v43, v226 dst_sel:DWORD dst_unused:UNUSED_PAD src0_sel:WORD_1 src1_sel:DWORD
	v_pk_mul_f32 v[44:45], v[34:35], v[44:45]
	v_and_b32_sdwa v47, v42, v226 dst_sel:DWORD dst_unused:UNUSED_PAD src0_sel:WORD_1 src1_sel:DWORD
	v_add3_u32 v42, v42, v47, s33
	v_add3_u32 v43, v43, v46, s33
	v_and_b32_sdwa v46, v45, v226 dst_sel:DWORD dst_unused:UNUSED_PAD src0_sel:WORD_1 src1_sel:DWORD
	v_and_b32_sdwa v47, v44, v226 dst_sel:DWORD dst_unused:UNUSED_PAD src0_sel:WORD_1 src1_sel:DWORD
	v_add3_u32 v45, v45, v46, s33
	v_add3_u32 v44, v44, v47, s33
	v_and_b32_e32 v45, 0xffff0000, v45
	v_and_b32_e32 v44, 0xffff0000, v44
	v_or_b32_sdwa v43, v45, v43 dst_sel:DWORD dst_unused:UNUSED_PAD src0_sel:DWORD src1_sel:WORD_1
	v_or_b32_sdwa v42, v44, v42 dst_sel:DWORD dst_unused:UNUSED_PAD src0_sel:DWORD src1_sel:WORD_1
	global_store_dwordx2 v[70:71], v[42:43], off offset:1024 sc1
	v_mov_b32_e32 v42, v38
	v_mov_b32_e32 v43, v40
	v_pk_mul_f32 v[42:43], v[42:43], v[2:3] op_sel_hi:[1,0]
	v_mov_b32_e32 v40, v39
	v_pk_mul_f32 v[42:43], v[8:9], v[42:43]
	v_pk_mul_f32 v[38:39], v[40:41], v[2:3] op_sel_hi:[1,0]
	v_and_b32_sdwa v40, v42, v226 dst_sel:DWORD dst_unused:UNUSED_PAD src0_sel:WORD_1 src1_sel:DWORD
	v_pk_mul_f32 v[38:39], v[74:75], v[38:39]
	v_add3_u32 v40, v42, v40, s33
	v_and_b32_sdwa v41, v39, v226 dst_sel:DWORD dst_unused:UNUSED_PAD src0_sel:WORD_1 src1_sel:DWORD
	v_and_b32_sdwa v42, v38, v226 dst_sel:DWORD dst_unused:UNUSED_PAD src0_sel:WORD_1 src1_sel:DWORD
	v_and_b32_sdwa v2, v43, v226 dst_sel:DWORD dst_unused:UNUSED_PAD src0_sel:WORD_1 src1_sel:DWORD
	v_add3_u32 v39, v39, v41, s33
	v_add3_u32 v38, v38, v42, s33
	v_add3_u32 v2, v43, v2, s33
	v_and_b32_e32 v39, 0xffff0000, v39
	v_and_b32_e32 v38, 0xffff0000, v38
	v_or_b32_sdwa v39, v39, v2 dst_sel:DWORD dst_unused:UNUSED_PAD src0_sel:DWORD src1_sel:WORD_1
	v_or_b32_sdwa v38, v38, v40 dst_sel:DWORD dst_unused:UNUSED_PAD src0_sel:DWORD src1_sel:WORD_1
.LBB0_1203:
	s_andn2_saveexec_b64 s[0:1], s[20:21]
	s_cbranch_execz .LBB0_1200
	v_mov_b64_e32 v[38:39], v[0:1]
	v_mov_b32_e32 v39, v0
	global_store_dwordx2 v[70:71], v[0:1], off offset:-2048 sc1
	global_store_dwordx2 v[70:71], v[0:1], off offset:-1536 sc1
	global_store_dwordx2 v[70:71], v[0:1], off offset:-1024 sc1
	global_store_dwordx2 v[70:71], v[0:1], off offset:-512 sc1
	global_store_dwordx2 v[70:71], v[0:1], off sc1
	global_store_dwordx2 v[70:71], v[0:1], off offset:512 sc1
	global_store_dwordx2 v[70:71], v[0:1], off offset:1024 sc1
	s_branch .LBB0_1200

; template <int EPI>
; __device__ __forceinline__ void gemm_tile(const u16* __restrict__ A, long lda, const u16* __restrict__ Bt, long ldb, int K,
;                                           int brow, int bcol, const Epi& e, u16* shm) {
;     ...
; #pragma unroll
;     for (int ai = 0; ai < 2; ++ai) {
; #pragma unroll
;       for (int bj = 0; bj < 2; ++bj)
; #pragma unroll
;       for (int m = 0; m < 4; ++m)
; #pragma unroll
;       for (int n = 0; n < 2; ++n)
; #pragma unroll
;         for (int j = 0; j < 4; ++j) {
;           float v = acc[ai][bj][m][n][j];
;           if constexpr (EPI == EPI_FFN1) { v = fmaxf(v, 0.f); v = v * v; }
;           Cs[(wr * 64 + m * 16 + fq * 4 + j) * 264 + bj * HALF + wc * 32 + n * 16 + fr] = f2bf(v);
;         }
.LBB0_1251:
	s_or_b64 exec, exec, s[0:1]
	v_mov_b32_e32 v138, v188
	s_waitcnt vmcnt(0)
	s_barrier
	s_movk_i32 s18, 0x210
	v_and_b32_e32 v0, 15, v138
	v_lshlrev_b32_e32 v141, 1, v0
	v_lshlrev_b32_e32 v0, 4, v138
	v_lshrrev_b32_e32 v1, 2, v138
	v_and_b32_e32 v2, 0x1f0, v0
	v_and_b32_e32 v139, 0xfffffcc, v1
	v_and_b32_e32 v1, 0xc0, v138
	v_add_u32_e32 v136, 0, v2
	v_ashrrev_i32_e32 v137, 5, v138
	v_add_u32_e32 v140, 0, v1
	v_mad_u64_u32 v[0:1], s[0:1], v137, s18, v[136:137]
	v_max_f32_e32 v1, v132, v132
	v_max_f32_e32 v1, 0, v1
	v_mul_f32_e32 v1, v1, v1
	v_bfe_u32 v132, v1, 16, 1
	v_add3_u32 v132, v1, v132, s33
	v_mul_lo_u32 v1, v139, s18
	v_add3_u32 v1, v140, v141, v1
	ds_write_b16_d16_hi v1, v132
	v_max_f32_e32 v132, v133, v133
	v_max_f32_e32 v132, 0, v132
	v_mul_f32_e32 v132, v132, v132
	v_bfe_u32 v133, v132, 16, 1
	v_add3_u32 v132, v132, v133, s33
	ds_write_b16_d16_hi v1, v132 offset:528
	v_max_f32_e32 v132, v134, v134
	v_max_f32_e32 v132, 0, v132
	v_mul_f32_e32 v132, v132, v132
	v_bfe_u32 v133, v132, 16, 1
	v_add3_u32 v132, v132, v133, s33
	ds_write_b16_d16_hi v1, v132 offset:1056
	v_max_f32_e32 v132, v135, v135
	v_max_f32_e32 v132, 0, v132
	v_mul_f32_e32 v132, v132, v132
	v_max_f32_e32 v128, v128, v128
	v_bfe_u32 v133, v132, 16, 1
	v_max_f32_e32 v128, 0, v128
	v_add3_u32 v132, v132, v133, s33
	v_mul_f32_e32 v128, v128, v128
	ds_write_b16_d16_hi v1, v132 offset:1584
	v_bfe_u32 v132, v128, 16, 1
	v_add3_u32 v128, v128, v132, s33
	ds_write_b16_d16_hi v1, v128 offset:32
	v_max_f32_e32 v128, v129, v129
	v_max_f32_e32 v128, 0, v128
	v_mul_f32_e32 v128, v128, v128
	v_bfe_u32 v129, v128, 16, 1
	v_add3_u32 v128, v128, v129, s33
	ds_write_b16_d16_hi v1, v128 offset:560
	v_max_f32_e32 v128, v130, v130
	v_max_f32_e32 v128, 0, v128
	v_mul_f32_e32 v128, v128, v128
	v_bfe_u32 v129, v128, 16, 1
	v_add3_u32 v128, v128, v129, s33
	ds_write_b16_d16_hi v1, v128 offset:1088
	v_max_f32_e32 v128, v131, v131
	v_max_f32_e32 v128, 0, v128
	v_mul_f32_e32 v128, v128, v128
	v_max_f32_e32 v124, v124, v124
	v_bfe_u32 v129, v128, 16, 1
	v_max_f32_e32 v124, 0, v124
	v_add3_u32 v128, v128, v129, s33
	v_mul_f32_e32 v124, v124, v124
	ds_write_b16_d16_hi v1, v128 offset:1616
	v_bfe_u32 v128, v124, 16, 1
	v_add3_u32 v124, v124, v128, s33
	ds_write_b16_d16_hi v1, v124 offset:8448
	v_max_f32_e32 v124, v125, v125
	v_max_f32_e32 v124, 0, v124
	v_mul_f32_e32 v124, v124, v124
	v_bfe_u32 v125, v124, 16, 1
	v_add3_u32 v124, v124, v125, s33
	ds_write_b16_d16_hi v1, v124 offset:8976
	v_max_f32_e32 v124, v126, v126
	v_max_f32_e32 v124, 0, v124
	v_mul_f32_e32 v124, v124, v124
	v_bfe_u32 v125, v124, 16, 1
	v_add3_u32 v124, v124, v125, s33
	ds_write_b16_d16_hi v1, v124 offset:9504
	v_max_f32_e32 v124, v127, v127
	v_max_f32_e32 v124, 0, v124
	v_mul_f32_e32 v124, v124, v124
	v_max_f32_e32 v120, v120, v120
	v_bfe_u32 v125, v124, 16, 1
	v_max_f32_e32 v120, 0, v120
	v_add3_u32 v124, v124, v125, s33
	v_mul_f32_e32 v120, v120, v120
	ds_write_b16_d16_hi v1, v124 offset:10032
	v_bfe_u32 v124, v120, 16, 1
	v_add3_u32 v120, v120, v124, s33
	ds_write_b16_d16_hi v1, v120 offset:8480
	v_max_f32_e32 v120, v121, v121
	v_max_f32_e32 v120, 0, v120
	v_mul_f32_e32 v120, v120, v120
	v_bfe_u32 v121, v120, 16, 1
	v_add3_u32 v120, v120, v121, s33
	ds_write_b16_d16_hi v1, v120 offset:9008
	v_max_f32_e32 v120, v122, v122
	v_max_f32_e32 v120, 0, v120
	v_mul_f32_e32 v120, v120, v120
	v_bfe_u32 v121, v120, 16, 1
	v_add3_u32 v120, v120, v121, s33
	ds_write_b16_d16_hi v1, v120 offset:9536
	v_max_f32_e32 v120, v123, v123
	v_max_f32_e32 v120, 0, v120
	v_mul_f32_e32 v120, v120, v120
	v_max_f32_e32 v116, v116, v116
	v_bfe_u32 v121, v120, 16, 1
	v_max_f32_e32 v116, 0, v116
	v_add3_u32 v120, v120, v121, s33
	v_mul_f32_e32 v116, v116, v116
	ds_write_b16_d16_hi v1, v120 offset:10064
	v_bfe_u32 v120, v116, 16, 1
	v_add3_u32 v116, v116, v120, s33
	ds_write_b16_d16_hi v1, v116 offset:16896
	v_max_f32_e32 v116, v117, v117
	v_max_f32_e32 v116, 0, v116
	v_mul_f32_e32 v116, v116, v116
	v_bfe_u32 v117, v116, 16, 1
	v_add3_u32 v116, v116, v117, s33
	ds_write_b16_d16_hi v1, v116 offset:17424
	v_max_f32_e32 v116, v118, v118
	v_max_f32_e32 v116, 0, v116
	v_mul_f32_e32 v116, v116, v116
	v_bfe_u32 v117, v116, 16, 1
	v_add3_u32 v116, v116, v117, s33
	ds_write_b16_d16_hi v1, v116 offset:17952
	v_max_f32_e32 v116, v119, v119
	v_max_f32_e32 v116, 0, v116
	v_mul_f32_e32 v116, v116, v116
	v_max_f32_e32 v112, v112, v112
	v_bfe_u32 v117, v116, 16, 1
	v_max_f32_e32 v112, 0, v112
	v_add3_u32 v116, v116, v117, s33
	v_mul_f32_e32 v112, v112, v112
	ds_write_b16_d16_hi v1, v116 offset:18480
	v_bfe_u32 v116, v112, 16, 1
	v_add3_u32 v112, v112, v116, s33
	ds_write_b16_d16_hi v1, v112 offset:16928
	v_max_f32_e32 v112, v113, v113
	v_max_f32_e32 v112, 0, v112
	v_mul_f32_e32 v112, v112, v112
	v_bfe_u32 v113, v112, 16, 1
	v_add3_u32 v112, v112, v113, s33
	ds_write_b16_d16_hi v1, v112 offset:17456
	v_max_f32_e32 v112, v114, v114
	v_max_f32_e32 v112, 0, v112
	v_mul_f32_e32 v112, v112, v112
	v_bfe_u32 v113, v112, 16, 1
	v_add3_u32 v112, v112, v113, s33
	ds_write_b16_d16_hi v1, v112 offset:17984
	v_max_f32_e32 v112, v115, v115
	v_max_f32_e32 v112, 0, v112
	v_mul_f32_e32 v112, v112, v112
	v_max_f32_e32 v108, v108, v108
	v_bfe_u32 v113, v112, 16, 1
	v_max_f32_e32 v108, 0, v108
	v_add3_u32 v112, v112, v113, s33
	v_mul_f32_e32 v108, v108, v108
	ds_write_b16_d16_hi v1, v112 offset:18512
	v_bfe_u32 v112, v108, 16, 1
	v_add3_u32 v108, v108, v112, s33
	ds_write_b16_d16_hi v1, v108 offset:25344
	v_max_f32_e32 v108, v109, v109
	v_max_f32_e32 v108, 0, v108
	v_mul_f32_e32 v108, v108, v108
	v_bfe_u32 v109, v108, 16, 1
	v_add3_u32 v108, v108, v109, s33
; template <int EPI>
; __device__ __forceinline__ void gemm_tile(const u16* __restrict__ A, long lda, const u16* __restrict__ Bt, long ldb, int K,
;                                           int brow, int bcol, const Epi& e, u16* shm) {
;     ...
; #pragma unroll
;     for (int ai = 0; ai < 2; ++ai) {
; #pragma unroll
;       for (int bj = 0; bj < 2; ++bj)
; #pragma unroll
;       for (int m = 0; m < 4; ++m)
; #pragma unroll
;       for (int n = 0; n < 2; ++n)
; #pragma unroll
;         for (int j = 0; j < 4; ++j) {
;           float v = acc[ai][bj][m][n][j];
;           if constexpr (EPI == EPI_FFN1) { v = fmaxf(v, 0.f); v = v * v; }
;           Cs[(wr * 64 + m * 16 + fq * 4 + j) * 264 + bj * HALF + wc * 32 + n * 16 + fr] = f2bf(v);
;         }
	ds_write_b16_d16_hi v1, v108 offset:25872
	v_max_f32_e32 v108, v110, v110
	v_max_f32_e32 v108, 0, v108
	v_mul_f32_e32 v108, v108, v108
	v_bfe_u32 v109, v108, 16, 1
	v_add3_u32 v108, v108, v109, s33
	ds_write_b16_d16_hi v1, v108 offset:26400
	v_max_f32_e32 v108, v111, v111
	v_max_f32_e32 v108, 0, v108
	v_mul_f32_e32 v108, v108, v108
	v_max_f32_e32 v104, v104, v104
	v_bfe_u32 v109, v108, 16, 1
	v_max_f32_e32 v104, 0, v104
	v_add3_u32 v108, v108, v109, s33
	v_mul_f32_e32 v104, v104, v104
	ds_write_b16_d16_hi v1, v108 offset:26928
	v_bfe_u32 v108, v104, 16, 1
	v_add3_u32 v104, v104, v108, s33
	ds_write_b16_d16_hi v1, v104 offset:25376
	v_max_f32_e32 v104, v105, v105
	v_max_f32_e32 v104, 0, v104
	v_mul_f32_e32 v104, v104, v104
	v_bfe_u32 v105, v104, 16, 1
	v_add3_u32 v104, v104, v105, s33
	ds_write_b16_d16_hi v1, v104 offset:25904
	v_max_f32_e32 v104, v106, v106
	v_max_f32_e32 v104, 0, v104
	v_mul_f32_e32 v104, v104, v104
	v_bfe_u32 v105, v104, 16, 1
	v_add3_u32 v104, v104, v105, s33
	ds_write_b16_d16_hi v1, v104 offset:26432
	v_max_f32_e32 v104, v107, v107
	v_max_f32_e32 v104, 0, v104
	v_mul_f32_e32 v104, v104, v104
	v_max_f32_e32 v100, v100, v100
	v_bfe_u32 v105, v104, 16, 1
	v_max_f32_e32 v100, 0, v100
	v_add3_u32 v104, v104, v105, s33
	v_mul_f32_e32 v100, v100, v100
	ds_write_b16_d16_hi v1, v104 offset:26960
	v_bfe_u32 v104, v100, 16, 1
	v_add3_u32 v100, v100, v104, s33
	ds_write_b16_d16_hi v1, v100 offset:256
	v_max_f32_e32 v100, v101, v101
	v_max_f32_e32 v100, 0, v100
	v_mul_f32_e32 v100, v100, v100
	v_bfe_u32 v101, v100, 16, 1
	v_add3_u32 v100, v100, v101, s33
	ds_write_b16_d16_hi v1, v100 offset:784
	v_max_f32_e32 v100, v102, v102
	v_max_f32_e32 v100, 0, v100
	v_mul_f32_e32 v100, v100, v100
	v_bfe_u32 v101, v100, 16, 1
	v_add3_u32 v100, v100, v101, s33
	ds_write_b16_d16_hi v1, v100 offset:1312
	v_max_f32_e32 v100, v103, v103
	v_max_f32_e32 v100, 0, v100
	v_mul_f32_e32 v100, v100, v100
	v_max_f32_e32 v96, v96, v96
	v_bfe_u32 v101, v100, 16, 1
	v_max_f32_e32 v96, 0, v96
	v_add3_u32 v100, v100, v101, s33
	v_mul_f32_e32 v96, v96, v96
	ds_write_b16_d16_hi v1, v100 offset:1840
	v_bfe_u32 v100, v96, 16, 1
	v_add3_u32 v96, v96, v100, s33
	ds_write_b16_d16_hi v1, v96 offset:288
	v_max_f32_e32 v96, v97, v97
	v_max_f32_e32 v96, 0, v96
	v_mul_f32_e32 v96, v96, v96
	v_bfe_u32 v97, v96, 16, 1
	v_add3_u32 v96, v96, v97, s33
	ds_write_b16_d16_hi v1, v96 offset:816
	v_max_f32_e32 v96, v98, v98
	v_max_f32_e32 v96, 0, v96
	v_mul_f32_e32 v96, v96, v96
	v_bfe_u32 v97, v96, 16, 1
	v_add3_u32 v96, v96, v97, s33
	ds_write_b16_d16_hi v1, v96 offset:1344
	v_max_f32_e32 v96, v99, v99
	v_max_f32_e32 v96, 0, v96
	v_mul_f32_e32 v96, v96, v96
	v_max_f32_e32 v92, v92, v92
	v_bfe_u32 v97, v96, 16, 1
	v_max_f32_e32 v92, 0, v92
	v_add3_u32 v96, v96, v97, s33
	v_mul_f32_e32 v92, v92, v92
	ds_write_b16_d16_hi v1, v96 offset:1872
	v_bfe_u32 v96, v92, 16, 1
	v_add3_u32 v92, v92, v96, s33
	ds_write_b16_d16_hi v1, v92 offset:8704
	v_max_f32_e32 v92, v93, v93
	v_max_f32_e32 v92, 0, v92
	v_mul_f32_e32 v92, v92, v92
	v_bfe_u32 v93, v92, 16, 1
	v_add3_u32 v92, v92, v93, s33
	ds_write_b16_d16_hi v1, v92 offset:9232
	v_max_f32_e32 v92, v94, v94
	v_max_f32_e32 v92, 0, v92
	v_mul_f32_e32 v92, v92, v92
	v_bfe_u32 v93, v92, 16, 1
	v_add3_u32 v92, v92, v93, s33
	ds_write_b16_d16_hi v1, v92 offset:9760
	v_max_f32_e32 v92, v95, v95
	v_max_f32_e32 v92, 0, v92
	v_mul_f32_e32 v92, v92, v92
	v_max_f32_e32 v88, v88, v88
	v_bfe_u32 v93, v92, 16, 1
	v_max_f32_e32 v88, 0, v88
	v_add3_u32 v92, v92, v93, s33
	v_mul_f32_e32 v88, v88, v88
	ds_write_b16_d16_hi v1, v92 offset:10288
	v_bfe_u32 v92, v88, 16, 1
	v_add3_u32 v88, v88, v92, s33
	ds_write_b16_d16_hi v1, v88 offset:8736
	v_max_f32_e32 v88, v89, v89
	v_max_f32_e32 v88, 0, v88
	v_mul_f32_e32 v88, v88, v88
	v_bfe_u32 v89, v88, 16, 1
	v_add3_u32 v88, v88, v89, s33
	ds_write_b16_d16_hi v1, v88 offset:9264
	v_max_f32_e32 v88, v90, v90
	v_max_f32_e32 v88, 0, v88
	v_mul_f32_e32 v88, v88, v88
	v_bfe_u32 v89, v88, 16, 1
	v_add3_u32 v88, v88, v89, s33
	ds_write_b16_d16_hi v1, v88 offset:9792
	v_max_f32_e32 v88, v91, v91
	v_max_f32_e32 v88, 0, v88
	v_mul_f32_e32 v88, v88, v88
	v_max_f32_e32 v84, v84, v84
	v_bfe_u32 v89, v88, 16, 1
	v_max_f32_e32 v84, 0, v84
	v_add3_u32 v88, v88, v89, s33
	v_mul_f32_e32 v84, v84, v84
	ds_write_b16_d16_hi v1, v88 offset:10320
	v_bfe_u32 v88, v84, 16, 1
	v_add3_u32 v84, v84, v88, s33
	ds_write_b16_d16_hi v1, v84 offset:17152
	v_max_f32_e32 v84, v85, v85
	v_max_f32_e32 v84, 0, v84
	v_mul_f32_e32 v84, v84, v84
	v_bfe_u32 v85, v84, 16, 1
	v_add3_u32 v84, v84, v85, s33
	ds_write_b16_d16_hi v1, v84 offset:17680
	v_max_f32_e32 v84, v86, v86
	v_max_f32_e32 v84, 0, v84
	v_mul_f32_e32 v84, v84, v84
	v_bfe_u32 v85, v84, 16, 1
	v_add3_u32 v84, v84, v85, s33
	ds_write_b16_d16_hi v1, v84 offset:18208
	v_max_f32_e32 v84, v87, v87
	v_max_f32_e32 v84, 0, v84
	v_mul_f32_e32 v84, v84, v84
	v_max_f32_e32 v80, v80, v80
	v_bfe_u32 v85, v84, 16, 1
	v_max_f32_e32 v80, 0, v80
	v_add3_u32 v84, v84, v85, s33
	v_mul_f32_e32 v80, v80, v80
	ds_write_b16_d16_hi v1, v84 offset:18736
	v_bfe_u32 v84, v80, 16, 1
	v_add3_u32 v80, v80, v84, s33
	ds_write_b16_d16_hi v1, v80 offset:17184
	v_max_f32_e32 v80, v81, v81
	v_max_f32_e32 v80, 0, v80
	v_mul_f32_e32 v80, v80, v80
	v_bfe_u32 v81, v80, 16, 1
	v_add3_u32 v80, v80, v81, s33
	ds_write_b16_d16_hi v1, v80 offset:17712
	v_max_f32_e32 v80, v82, v82
	v_max_f32_e32 v80, 0, v80
	v_mul_f32_e32 v80, v80, v80
	v_bfe_u32 v81, v80, 16, 1
	v_add3_u32 v80, v80, v81, s33
	ds_write_b16_d16_hi v1, v80 offset:18240
	v_max_f32_e32 v80, v83, v83
	v_max_f32_e32 v80, 0, v80
	v_mul_f32_e32 v80, v80, v80
	v_max_f32_e32 v76, v76, v76
; template <int EPI>
; __device__ __forceinline__ void gemm_tile(const u16* __restrict__ A, long lda, const u16* __restrict__ Bt, long ldb, int K,
;                                           int brow, int bcol, const Epi& e, u16* shm) {
;     ...
;         for (int j = 0; j < 4; ++j) {
;           float v = acc[ai][bj][m][n][j];
;           if constexpr (EPI == EPI_FFN1) { v = fmaxf(v, 0.f); v = v * v; }
;           Cs[(wr * 64 + m * 16 + fq * 4 + j) * 264 + bj * HALF + wc * 32 + n * 16 + fr] = f2bf(v);
;         }
;       __syncthreads();
; #pragma unroll
;       for (int i = 0; i < 8; ++i) {
;         const int idx = tx + 512 * i, rl = idx >> 5, cv = idx & 31;
;         typedef __attribute__((ext_vector_type(4))) unsigned u32x4;
;         const u32x4 v = *(const u32x4*)(Cs + rl * 264 + cv * 8);
;         __builtin_nontemporal_store(v, (u32x4*)(e.cb + (long)(brow + ai * HALF + rl) * ldc + bcol + cv * 8));
;       }
	v_bfe_u32 v81, v80, 16, 1
	v_max_f32_e32 v76, 0, v76
	v_add3_u32 v80, v80, v81, s33
	v_mul_f32_e32 v76, v76, v76
	ds_write_b16_d16_hi v1, v80 offset:18768
	v_bfe_u32 v80, v76, 16, 1
	v_add3_u32 v76, v76, v80, s33
	ds_write_b16_d16_hi v1, v76 offset:25600
	v_max_f32_e32 v76, v77, v77
	v_max_f32_e32 v76, 0, v76
	v_mul_f32_e32 v76, v76, v76
	v_bfe_u32 v77, v76, 16, 1
	v_add3_u32 v76, v76, v77, s33
	ds_write_b16_d16_hi v1, v76 offset:26128
	v_max_f32_e32 v76, v78, v78
	v_max_f32_e32 v76, 0, v76
	v_mul_f32_e32 v76, v76, v76
	v_bfe_u32 v77, v76, 16, 1
	v_add3_u32 v76, v76, v77, s33
	ds_write_b16_d16_hi v1, v76 offset:26656
	v_max_f32_e32 v76, v79, v79
	v_max_f32_e32 v76, 0, v76
	v_mul_f32_e32 v76, v76, v76
	v_max_f32_e32 v72, v72, v72
	v_bfe_u32 v77, v76, 16, 1
	v_max_f32_e32 v72, 0, v72
	v_add3_u32 v76, v76, v77, s33
	v_mul_f32_e32 v72, v72, v72
	ds_write_b16_d16_hi v1, v76 offset:27184
	v_bfe_u32 v76, v72, 16, 1
	v_add3_u32 v72, v72, v76, s33
	ds_write_b16_d16_hi v1, v72 offset:25632
	v_max_f32_e32 v72, v73, v73
	v_max_f32_e32 v72, 0, v72
	v_mul_f32_e32 v72, v72, v72
	v_bfe_u32 v73, v72, 16, 1
	v_add3_u32 v72, v72, v73, s33
	ds_write_b16_d16_hi v1, v72 offset:26160
	v_max_f32_e32 v72, v74, v74
	v_max_f32_e32 v72, 0, v72
	v_mul_f32_e32 v72, v72, v72
	v_bfe_u32 v73, v72, 16, 1
	v_add3_u32 v72, v72, v73, s33
	ds_write_b16_d16_hi v1, v72 offset:26688
	v_max_f32_e32 v72, v75, v75
	v_max_f32_e32 v72, 0, v72
	v_mul_f32_e32 v72, v72, v72
	v_bfe_u32 v73, v72, 16, 1
	v_add3_u32 v72, v72, v73, s33
	ds_write_b16_d16_hi v1, v72 offset:27216
	v_add_u32_e32 v72, s39, v137
	v_ashrrev_i32_e32 v73, 31, v72
	v_lshlrev_b64 v[72:73], 14, v[72:73]
	s_waitcnt lgkmcnt(0)
	s_barrier
	ds_read_b128 v[74:77], v0
	v_lshl_add_u64 v[72:73], s[4:5], 0, v[72:73]
	s_lshl_b64 s[12:13], s[12:13], 1
	v_lshl_add_u64 v[72:73], v[72:73], 0, s[12:13]
	v_lshl_add_u64 v[82:83], v[72:73], 0, v[2:3]
	v_add_u32_e32 v72, 0x200, v138
	v_ashrrev_i32_e32 v96, 5, v72
	v_mad_u64_u32 v[72:73], s[0:1], v96, s18, v[136:137]
	ds_read_b128 v[78:81], v72
	s_waitcnt lgkmcnt(1)
	global_store_dwordx4 v[82:83], v[74:77], off sc1
	v_add_u32_e32 v73, 0x400, v138
	v_ashrrev_i32_e32 v73, 5, v73
	v_add_u32_e32 v74, s39, v96
	v_ashrrev_i32_e32 v75, 31, v74
	v_lshlrev_b64 v[74:75], 14, v[74:75]
	v_lshl_add_u64 v[74:75], s[4:5], 0, v[74:75]
	v_lshl_add_u64 v[74:75], v[74:75], 0, s[12:13]
	v_lshl_add_u64 v[74:75], v[74:75], 0, v[2:3]
	s_waitcnt lgkmcnt(0)
	global_store_dwordx4 v[74:75], v[78:81], off sc1
	v_mad_u64_u32 v[74:75], s[0:1], v73, s18, v[136:137]
	v_add_u32_e32 v76, s39, v73
	ds_read_b128 v[78:81], v74
	v_ashrrev_i32_e32 v77, 31, v76
	v_lshlrev_b64 v[76:77], 14, v[76:77]
	v_lshl_add_u64 v[76:77], s[4:5], 0, v[76:77]
	v_add_u32_e32 v75, 0x600, v138
	v_lshl_add_u64 v[76:77], v[76:77], 0, s[12:13]
	v_ashrrev_i32_e32 v75, 5, v75
	v_lshl_add_u64 v[86:87], v[76:77], 0, v[2:3]
	v_mad_u64_u32 v[76:77], s[0:1], v75, s18, v[136:137]
	ds_read_b128 v[82:85], v76
	s_waitcnt lgkmcnt(1)
	global_store_dwordx4 v[86:87], v[78:81], off sc1
	v_add_u32_e32 v77, 0x800, v138
	v_ashrrev_i32_e32 v77, 5, v77
	v_add_u32_e32 v78, s39, v75
	v_ashrrev_i32_e32 v79, 31, v78
	v_lshlrev_b64 v[78:79], 14, v[78:79]
	v_lshl_add_u64 v[78:79], s[4:5], 0, v[78:79]
	v_lshl_add_u64 v[78:79], v[78:79], 0, s[12:13]
	v_lshl_add_u64 v[78:79], v[78:79], 0, v[2:3]
	s_waitcnt lgkmcnt(0)
	global_store_dwordx4 v[78:79], v[82:85], off sc1
	v_mad_u64_u32 v[78:79], s[0:1], v77, s18, v[136:137]
	v_add_u32_e32 v80, s39, v77
	ds_read_b128 v[82:85], v78
	v_ashrrev_i32_e32 v81, 31, v80
	v_lshlrev_b64 v[80:81], 14, v[80:81]
	v_lshl_add_u64 v[80:81], s[4:5], 0, v[80:81]
	v_add_u32_e32 v79, 0xa00, v138
	v_lshl_add_u64 v[80:81], v[80:81], 0, s[12:13]
	v_ashrrev_i32_e32 v79, 5, v79
	v_lshl_add_u64 v[90:91], v[80:81], 0, v[2:3]
	v_mad_u64_u32 v[80:81], s[0:1], v79, s18, v[136:137]
	ds_read_b128 v[86:89], v80
	s_waitcnt lgkmcnt(1)
	global_store_dwordx4 v[90:91], v[82:85], off sc1
	v_add_u32_e32 v81, 0xc00, v138
	v_ashrrev_i32_e32 v81, 5, v81
	v_add_u32_e32 v82, s39, v79
	v_ashrrev_i32_e32 v83, 31, v82
	v_lshlrev_b64 v[82:83], 14, v[82:83]
	v_lshl_add_u64 v[82:83], s[4:5], 0, v[82:83]
	v_lshl_add_u64 v[82:83], v[82:83], 0, s[12:13]
	v_lshl_add_u64 v[82:83], v[82:83], 0, v[2:3]
	s_waitcnt lgkmcnt(0)
	global_store_dwordx4 v[82:83], v[86:89], off sc1
	v_mad_u64_u32 v[82:83], s[0:1], v81, s18, v[136:137]
	v_add_u32_e32 v84, s39, v81
	ds_read_b128 v[86:89], v82
	v_ashrrev_i32_e32 v85, 31, v84
	v_lshlrev_b64 v[84:85], 14, v[84:85]
	v_lshl_add_u64 v[84:85], s[4:5], 0, v[84:85]
	v_add_u32_e32 v83, 0xe00, v138
	v_lshl_add_u64 v[84:85], v[84:85], 0, s[12:13]
	v_ashrrev_i32_e32 v83, 5, v83
	v_lshl_add_u64 v[94:95], v[84:85], 0, v[2:3]
	v_mad_u64_u32 v[84:85], s[0:1], v83, s18, v[136:137]
	ds_read_b128 v[90:93], v84
	s_waitcnt lgkmcnt(1)
	global_store_dwordx4 v[94:95], v[86:89], off sc1
	v_max_f32_e32 v68, v68, v68
	v_max_f32_e32 v68, 0, v68
	v_add_u32_e32 v86, s39, v83
	v_ashrrev_i32_e32 v87, 31, v86
	v_lshlrev_b64 v[86:87], 14, v[86:87]
	v_lshl_add_u64 v[86:87], s[4:5], 0, v[86:87]
	v_mul_f32_e32 v68, v68, v68
	v_lshl_add_u64 v[86:87], v[86:87], 0, s[12:13]
	v_bfe_u32 v85, v68, 16, 1
	v_lshl_add_u64 v[86:87], v[86:87], 0, v[2:3]
	v_add3_u32 v68, v68, v85, s33
	s_waitcnt lgkmcnt(0)
	global_store_dwordx4 v[86:87], v[90:93], off sc1
	s_barrier
; template <int EPI>
; __device__ __forceinline__ void gemm_tile(const u16* __restrict__ A, long lda, const u16* __restrict__ Bt, long ldb, int K,
;                                           int brow, int bcol, const Epi& e, u16* shm) {
;     ...
; #pragma unroll
;     for (int ai = 0; ai < 2; ++ai) {
; #pragma unroll
;       for (int bj = 0; bj < 2; ++bj)
; #pragma unroll
;       for (int m = 0; m < 4; ++m)
; #pragma unroll
;       for (int n = 0; n < 2; ++n)
; #pragma unroll
;         for (int j = 0; j < 4; ++j) {
;           float v = acc[ai][bj][m][n][j];
;           if constexpr (EPI == EPI_FFN1) { v = fmaxf(v, 0.f); v = v * v; }
;           Cs[(wr * 64 + m * 16 + fq * 4 + j) * 264 + bj * HALF + wc * 32 + n * 16 + fr] = f2bf(v);
;         }
	ds_write_b16_d16_hi v1, v68
	v_max_f32_e32 v68, v69, v69
	v_max_f32_e32 v68, 0, v68
	v_mul_f32_e32 v68, v68, v68
	v_bfe_u32 v69, v68, 16, 1
	v_add3_u32 v68, v68, v69, s33
	ds_write_b16_d16_hi v1, v68 offset:528
	v_max_f32_e32 v68, v70, v70
	v_max_f32_e32 v68, 0, v68
	v_mul_f32_e32 v68, v68, v68
	v_bfe_u32 v69, v68, 16, 1
	v_add3_u32 v68, v68, v69, s33
	ds_write_b16_d16_hi v1, v68 offset:1056
	v_max_f32_e32 v68, v71, v71
	v_max_f32_e32 v68, 0, v68
	v_mul_f32_e32 v68, v68, v68
	v_max_f32_e32 v64, v64, v64
	v_bfe_u32 v69, v68, 16, 1
	v_max_f32_e32 v64, 0, v64
	v_add3_u32 v68, v68, v69, s33
	v_mul_f32_e32 v64, v64, v64
	ds_write_b16_d16_hi v1, v68 offset:1584
	v_bfe_u32 v68, v64, 16, 1
	v_add3_u32 v64, v64, v68, s33
	ds_write_b16_d16_hi v1, v64 offset:32
	v_max_f32_e32 v64, v65, v65
	v_max_f32_e32 v64, 0, v64
	v_mul_f32_e32 v64, v64, v64
	v_bfe_u32 v65, v64, 16, 1
	v_add3_u32 v64, v64, v65, s33
	ds_write_b16_d16_hi v1, v64 offset:560
	v_max_f32_e32 v64, v66, v66
	v_max_f32_e32 v64, 0, v64
	v_mul_f32_e32 v64, v64, v64
	v_bfe_u32 v65, v64, 16, 1
	v_add3_u32 v64, v64, v65, s33
	ds_write_b16_d16_hi v1, v64 offset:1088
	v_max_f32_e32 v64, v67, v67
	v_max_f32_e32 v64, 0, v64
	v_mul_f32_e32 v64, v64, v64
	v_max_f32_e32 v60, v60, v60
	v_bfe_u32 v65, v64, 16, 1
	v_max_f32_e32 v60, 0, v60
	v_add3_u32 v64, v64, v65, s33
	v_mul_f32_e32 v60, v60, v60
	ds_write_b16_d16_hi v1, v64 offset:1616
	v_bfe_u32 v64, v60, 16, 1
	v_add3_u32 v60, v60, v64, s33
	ds_write_b16_d16_hi v1, v60 offset:8448
	v_max_f32_e32 v60, v61, v61
	v_max_f32_e32 v60, 0, v60
	v_mul_f32_e32 v60, v60, v60
	v_bfe_u32 v61, v60, 16, 1
	v_add3_u32 v60, v60, v61, s33
	ds_write_b16_d16_hi v1, v60 offset:8976
	v_max_f32_e32 v60, v62, v62
	v_max_f32_e32 v60, 0, v60
	v_mul_f32_e32 v60, v60, v60
	v_bfe_u32 v61, v60, 16, 1
	v_add3_u32 v60, v60, v61, s33
	ds_write_b16_d16_hi v1, v60 offset:9504
	v_max_f32_e32 v60, v63, v63
	v_max_f32_e32 v60, 0, v60
	v_mul_f32_e32 v60, v60, v60
	v_max_f32_e32 v56, v56, v56
	v_bfe_u32 v61, v60, 16, 1
	v_max_f32_e32 v56, 0, v56
	v_add3_u32 v60, v60, v61, s33
	v_mul_f32_e32 v56, v56, v56
	ds_write_b16_d16_hi v1, v60 offset:10032
	v_bfe_u32 v60, v56, 16, 1
	v_add3_u32 v56, v56, v60, s33
	ds_write_b16_d16_hi v1, v56 offset:8480
	v_max_f32_e32 v56, v57, v57
	v_max_f32_e32 v56, 0, v56
	v_mul_f32_e32 v56, v56, v56
	v_bfe_u32 v57, v56, 16, 1
	v_add3_u32 v56, v56, v57, s33
	ds_write_b16_d16_hi v1, v56 offset:9008
	v_max_f32_e32 v56, v58, v58
	v_max_f32_e32 v56, 0, v56
	v_mul_f32_e32 v56, v56, v56
	v_bfe_u32 v57, v56, 16, 1
	v_add3_u32 v56, v56, v57, s33
	ds_write_b16_d16_hi v1, v56 offset:9536
	v_max_f32_e32 v56, v59, v59
	v_max_f32_e32 v56, 0, v56
	v_mul_f32_e32 v56, v56, v56
	v_max_f32_e32 v52, v52, v52
	v_bfe_u32 v57, v56, 16, 1
	v_max_f32_e32 v52, 0, v52
	v_add3_u32 v56, v56, v57, s33
	v_mul_f32_e32 v52, v52, v52
	ds_write_b16_d16_hi v1, v56 offset:10064
	v_bfe_u32 v56, v52, 16, 1
	v_add3_u32 v52, v52, v56, s33
	ds_write_b16_d16_hi v1, v52 offset:16896
	v_max_f32_e32 v52, v53, v53
	v_max_f32_e32 v52, 0, v52
	v_mul_f32_e32 v52, v52, v52
	v_bfe_u32 v53, v52, 16, 1
	v_add3_u32 v52, v52, v53, s33
	ds_write_b16_d16_hi v1, v52 offset:17424
	v_max_f32_e32 v52, v54, v54
	v_max_f32_e32 v52, 0, v52
	v_mul_f32_e32 v52, v52, v52
	v_bfe_u32 v53, v52, 16, 1
	v_add3_u32 v52, v52, v53, s33
	ds_write_b16_d16_hi v1, v52 offset:17952
	v_max_f32_e32 v52, v55, v55
	v_max_f32_e32 v52, 0, v52
	v_mul_f32_e32 v52, v52, v52
	v_max_f32_e32 v48, v48, v48
	v_bfe_u32 v53, v52, 16, 1
	v_max_f32_e32 v48, 0, v48
	v_add3_u32 v52, v52, v53, s33
	v_mul_f32_e32 v48, v48, v48
	ds_write_b16_d16_hi v1, v52 offset:18480
	v_bfe_u32 v52, v48, 16, 1
	v_add3_u32 v48, v48, v52, s33
	ds_write_b16_d16_hi v1, v48 offset:16928
	v_max_f32_e32 v48, v49, v49
	v_max_f32_e32 v48, 0, v48
	v_mul_f32_e32 v48, v48, v48
	v_bfe_u32 v49, v48, 16, 1
	v_add3_u32 v48, v48, v49, s33
	ds_write_b16_d16_hi v1, v48 offset:17456
	v_max_f32_e32 v48, v50, v50
	v_max_f32_e32 v48, 0, v48
	v_mul_f32_e32 v48, v48, v48
	v_bfe_u32 v49, v48, 16, 1
	v_add3_u32 v48, v48, v49, s33
	ds_write_b16_d16_hi v1, v48 offset:17984
	v_max_f32_e32 v48, v51, v51
	v_max_f32_e32 v48, 0, v48
	v_mul_f32_e32 v48, v48, v48
	v_max_f32_e32 v44, v44, v44
	v_bfe_u32 v49, v48, 16, 1
	v_max_f32_e32 v44, 0, v44
	v_add3_u32 v48, v48, v49, s33
	v_mul_f32_e32 v44, v44, v44
	ds_write_b16_d16_hi v1, v48 offset:18512
	v_bfe_u32 v48, v44, 16, 1
	v_add3_u32 v44, v44, v48, s33
	ds_write_b16_d16_hi v1, v44 offset:25344
	v_max_f32_e32 v44, v45, v45
	v_max_f32_e32 v44, 0, v44
	v_mul_f32_e32 v44, v44, v44
	v_bfe_u32 v45, v44, 16, 1
	v_add3_u32 v44, v44, v45, s33
	ds_write_b16_d16_hi v1, v44 offset:25872
	v_max_f32_e32 v44, v46, v46
	v_max_f32_e32 v44, 0, v44
	v_mul_f32_e32 v44, v44, v44
	v_bfe_u32 v45, v44, 16, 1
	v_add3_u32 v44, v44, v45, s33
	ds_write_b16_d16_hi v1, v44 offset:26400
	v_max_f32_e32 v44, v47, v47
	v_max_f32_e32 v44, 0, v44
	v_mul_f32_e32 v44, v44, v44
	v_max_f32_e32 v40, v40, v40
	v_bfe_u32 v45, v44, 16, 1
	v_max_f32_e32 v40, 0, v40
	v_add3_u32 v44, v44, v45, s33
	v_mul_f32_e32 v40, v40, v40
	ds_write_b16_d16_hi v1, v44 offset:26928
	v_bfe_u32 v44, v40, 16, 1
	v_add3_u32 v40, v40, v44, s33
	ds_write_b16_d16_hi v1, v40 offset:25376
	v_max_f32_e32 v40, v41, v41
	v_max_f32_e32 v40, 0, v40
	v_mul_f32_e32 v40, v40, v40
	v_bfe_u32 v41, v40, 16, 1
	v_add3_u32 v40, v40, v41, s33
	ds_write_b16_d16_hi v1, v40 offset:25904
	v_max_f32_e32 v40, v42, v42
	v_max_f32_e32 v40, 0, v40
	v_mul_f32_e32 v40, v40, v40
	v_bfe_u32 v41, v40, 16, 1
	v_add3_u32 v40, v40, v41, s33
	ds_write_b16_d16_hi v1, v40 offset:26432
	v_max_f32_e32 v40, v43, v43
	v_max_f32_e32 v40, 0, v40
	v_mul_f32_e32 v40, v40, v40
; template <int EPI>
; __device__ __forceinline__ void gemm_tile(const u16* __restrict__ A, long lda, const u16* __restrict__ Bt, long ldb, int K,
;                                           int brow, int bcol, const Epi& e, u16* shm) {
;     ...
; #pragma unroll
;     for (int ai = 0; ai < 2; ++ai) {
; #pragma unroll
;       for (int bj = 0; bj < 2; ++bj)
; #pragma unroll
;       for (int m = 0; m < 4; ++m)
; #pragma unroll
;       for (int n = 0; n < 2; ++n)
; #pragma unroll
;         for (int j = 0; j < 4; ++j) {
;           float v = acc[ai][bj][m][n][j];
;           if constexpr (EPI == EPI_FFN1) { v = fmaxf(v, 0.f); v = v * v; }
;           Cs[(wr * 64 + m * 16 + fq * 4 + j) * 264 + bj * HALF + wc * 32 + n * 16 + fr] = f2bf(v);
;         }
;       __syncthreads();
	v_max_f32_e32 v36, v36, v36
	v_bfe_u32 v41, v40, 16, 1
	v_max_f32_e32 v36, 0, v36
	v_add3_u32 v40, v40, v41, s33
	v_mul_f32_e32 v36, v36, v36
	ds_write_b16_d16_hi v1, v40 offset:26960
	v_bfe_u32 v40, v36, 16, 1
	v_add3_u32 v36, v36, v40, s33
	ds_write_b16_d16_hi v1, v36 offset:256
	v_max_f32_e32 v36, v37, v37
	v_max_f32_e32 v36, 0, v36
	v_mul_f32_e32 v36, v36, v36
	v_bfe_u32 v37, v36, 16, 1
	v_add3_u32 v36, v36, v37, s33
	ds_write_b16_d16_hi v1, v36 offset:784
	v_max_f32_e32 v36, v38, v38
	v_max_f32_e32 v36, 0, v36
	v_mul_f32_e32 v36, v36, v36
	v_bfe_u32 v37, v36, 16, 1
	v_add3_u32 v36, v36, v37, s33
	ds_write_b16_d16_hi v1, v36 offset:1312
	v_max_f32_e32 v36, v39, v39
	v_max_f32_e32 v36, 0, v36
	v_mul_f32_e32 v36, v36, v36
	v_max_f32_e32 v32, v32, v32
	v_bfe_u32 v37, v36, 16, 1
	v_max_f32_e32 v32, 0, v32
	v_add3_u32 v36, v36, v37, s33
	v_mul_f32_e32 v32, v32, v32
	ds_write_b16_d16_hi v1, v36 offset:1840
	v_bfe_u32 v36, v32, 16, 1
	v_add3_u32 v32, v32, v36, s33
	ds_write_b16_d16_hi v1, v32 offset:288
	v_max_f32_e32 v32, v33, v33
	v_max_f32_e32 v32, 0, v32
	v_mul_f32_e32 v32, v32, v32
	v_bfe_u32 v33, v32, 16, 1
	v_add3_u32 v32, v32, v33, s33
	ds_write_b16_d16_hi v1, v32 offset:816
	v_max_f32_e32 v32, v34, v34
	v_max_f32_e32 v32, 0, v32
	v_mul_f32_e32 v32, v32, v32
	v_bfe_u32 v33, v32, 16, 1
	v_add3_u32 v32, v32, v33, s33
	ds_write_b16_d16_hi v1, v32 offset:1344
	v_max_f32_e32 v32, v35, v35
	v_max_f32_e32 v32, 0, v32
	v_mul_f32_e32 v32, v32, v32
	v_max_f32_e32 v28, v28, v28
	v_bfe_u32 v33, v32, 16, 1
	v_max_f32_e32 v28, 0, v28
	v_add3_u32 v32, v32, v33, s33
	v_mul_f32_e32 v28, v28, v28
	ds_write_b16_d16_hi v1, v32 offset:1872
	v_bfe_u32 v32, v28, 16, 1
	v_add3_u32 v28, v28, v32, s33
	ds_write_b16_d16_hi v1, v28 offset:8704
	v_max_f32_e32 v28, v29, v29
	v_max_f32_e32 v28, 0, v28
	v_mul_f32_e32 v28, v28, v28
	v_bfe_u32 v29, v28, 16, 1
	v_add3_u32 v28, v28, v29, s33
	ds_write_b16_d16_hi v1, v28 offset:9232
	v_max_f32_e32 v28, v30, v30
	v_max_f32_e32 v28, 0, v28
	v_mul_f32_e32 v28, v28, v28
	v_bfe_u32 v29, v28, 16, 1
	v_add3_u32 v28, v28, v29, s33
	ds_write_b16_d16_hi v1, v28 offset:9760
	v_max_f32_e32 v28, v31, v31
	v_max_f32_e32 v28, 0, v28
	v_mul_f32_e32 v28, v28, v28
	v_max_f32_e32 v24, v24, v24
	v_bfe_u32 v29, v28, 16, 1
	v_max_f32_e32 v24, 0, v24
	v_add3_u32 v28, v28, v29, s33
	v_mul_f32_e32 v24, v24, v24
	ds_write_b16_d16_hi v1, v28 offset:10288
	v_bfe_u32 v28, v24, 16, 1
	v_add3_u32 v24, v24, v28, s33
	ds_write_b16_d16_hi v1, v24 offset:8736
	v_max_f32_e32 v24, v25, v25
	v_max_f32_e32 v24, 0, v24
	v_mul_f32_e32 v24, v24, v24
	v_bfe_u32 v25, v24, 16, 1
	v_add3_u32 v24, v24, v25, s33
	ds_write_b16_d16_hi v1, v24 offset:9264
	v_max_f32_e32 v24, v26, v26
	v_max_f32_e32 v24, 0, v24
	v_mul_f32_e32 v24, v24, v24
	v_bfe_u32 v25, v24, 16, 1
	v_add3_u32 v24, v24, v25, s33
	ds_write_b16_d16_hi v1, v24 offset:9792
	v_max_f32_e32 v24, v27, v27
	v_max_f32_e32 v24, 0, v24
	v_mul_f32_e32 v24, v24, v24
	v_max_f32_e32 v20, v20, v20
	v_bfe_u32 v25, v24, 16, 1
	v_max_f32_e32 v20, 0, v20
	v_add3_u32 v24, v24, v25, s33
	v_mul_f32_e32 v20, v20, v20
	ds_write_b16_d16_hi v1, v24 offset:10320
	v_bfe_u32 v24, v20, 16, 1
	v_add3_u32 v20, v20, v24, s33
	ds_write_b16_d16_hi v1, v20 offset:17152
	v_max_f32_e32 v20, v21, v21
	v_max_f32_e32 v20, 0, v20
	v_mul_f32_e32 v20, v20, v20
	v_bfe_u32 v21, v20, 16, 1
	v_add3_u32 v20, v20, v21, s33
	ds_write_b16_d16_hi v1, v20 offset:17680
	v_max_f32_e32 v20, v22, v22
	v_max_f32_e32 v20, 0, v20
	v_mul_f32_e32 v20, v20, v20
	v_bfe_u32 v21, v20, 16, 1
	v_add3_u32 v20, v20, v21, s33
	ds_write_b16_d16_hi v1, v20 offset:18208
	v_max_f32_e32 v20, v23, v23
	v_max_f32_e32 v20, 0, v20
	v_mul_f32_e32 v20, v20, v20
	v_max_f32_e32 v16, v16, v16
	v_bfe_u32 v21, v20, 16, 1
	v_max_f32_e32 v16, 0, v16
	v_add3_u32 v20, v20, v21, s33
	v_mul_f32_e32 v16, v16, v16
	ds_write_b16_d16_hi v1, v20 offset:18736
	v_bfe_u32 v20, v16, 16, 1
	v_add3_u32 v16, v16, v20, s33
	ds_write_b16_d16_hi v1, v16 offset:17184
	v_max_f32_e32 v16, v17, v17
	v_max_f32_e32 v16, 0, v16
	v_mul_f32_e32 v16, v16, v16
	v_bfe_u32 v17, v16, 16, 1
	v_add3_u32 v16, v16, v17, s33
	ds_write_b16_d16_hi v1, v16 offset:17712
	v_max_f32_e32 v16, v18, v18
	v_max_f32_e32 v16, 0, v16
	v_mul_f32_e32 v16, v16, v16
	v_bfe_u32 v17, v16, 16, 1
	v_add3_u32 v16, v16, v17, s33
	ds_write_b16_d16_hi v1, v16 offset:18240
	v_max_f32_e32 v16, v19, v19
	v_max_f32_e32 v16, 0, v16
	v_mul_f32_e32 v16, v16, v16
	v_max_f32_e32 v12, v12, v12
	v_bfe_u32 v17, v16, 16, 1
	v_max_f32_e32 v12, 0, v12
	v_add3_u32 v16, v16, v17, s33
	v_mul_f32_e32 v12, v12, v12
	ds_write_b16_d16_hi v1, v16 offset:18768
	v_bfe_u32 v16, v12, 16, 1
	v_add3_u32 v12, v12, v16, s33
	ds_write_b16_d16_hi v1, v12 offset:25600
	v_max_f32_e32 v12, v13, v13
	v_max_f32_e32 v12, 0, v12
	v_mul_f32_e32 v12, v12, v12
	v_bfe_u32 v13, v12, 16, 1
	v_add3_u32 v12, v12, v13, s33
	ds_write_b16_d16_hi v1, v12 offset:26128
	v_max_f32_e32 v12, v14, v14
	v_max_f32_e32 v12, 0, v12
	v_mul_f32_e32 v12, v12, v12
	v_bfe_u32 v13, v12, 16, 1
	v_add3_u32 v12, v12, v13, s33
	ds_write_b16_d16_hi v1, v12 offset:26656
	v_max_f32_e32 v12, v15, v15
	v_max_f32_e32 v12, 0, v12
	v_mul_f32_e32 v12, v12, v12
	v_max_f32_e32 v8, v8, v8
	v_bfe_u32 v13, v12, 16, 1
	v_max_f32_e32 v8, 0, v8
	v_add3_u32 v12, v12, v13, s33
	v_mul_f32_e32 v8, v8, v8
	ds_write_b16_d16_hi v1, v12 offset:27184
	v_bfe_u32 v12, v8, 16, 1
	v_add3_u32 v8, v8, v12, s33
	ds_write_b16_d16_hi v1, v8 offset:25632
	v_max_f32_e32 v8, v9, v9
	v_max_f32_e32 v8, 0, v8
	v_mul_f32_e32 v8, v8, v8
	v_bfe_u32 v9, v8, 16, 1
	v_add3_u32 v8, v8, v9, s33
	ds_write_b16_d16_hi v1, v8 offset:26160
	v_max_f32_e32 v8, v10, v10
	v_max_f32_e32 v8, 0, v8
	v_mul_f32_e32 v8, v8, v8
	v_bfe_u32 v9, v8, 16, 1
	v_add3_u32 v8, v8, v9, s33
	ds_write_b16_d16_hi v1, v8 offset:26688
	v_max_f32_e32 v8, v11, v11
	v_max_f32_e32 v8, 0, v8
	v_mul_f32_e32 v8, v8, v8
	v_bfe_u32 v9, v8, 16, 1
	v_add3_u32 v8, v8, v9, s33
	ds_write_b16_d16_hi v1, v8 offset:27216
	s_waitcnt lgkmcnt(0)
	s_barrier
; template <int EPI>
; __device__ __forceinline__ void gemm_tile(const u16* __restrict__ A, long lda, const u16* __restrict__ Bt, long ldb, int K,
;                                           int brow, int bcol, const Epi& e, u16* shm) {
;     ...
;       __syncthreads();
; #pragma unroll
;       for (int i = 0; i < 8; ++i) {
;         const int idx = tx + 512 * i, rl = idx >> 5, cv = idx & 31;
;         typedef __attribute__((ext_vector_type(4))) unsigned u32x4;
;         const u32x4 v = *(const u32x4*)(Cs + rl * 264 + cv * 8);
;         __builtin_nontemporal_store(v, (u32x4*)(e.cb + (long)(brow + ai * HALF + rl) * ldc + bcol + cv * 8));
;       }
;       __syncthreads();
	ds_read_b128 v[8:11], v0
	ds_read_b128 v[12:15], v72
	v_add_u32_e32 v0, s38, v137
	v_ashrrev_i32_e32 v1, 31, v0
	v_lshlrev_b64 v[0:1], 14, v[0:1]
	v_lshl_add_u64 v[0:1], s[4:5], 0, v[0:1]
	v_lshl_add_u64 v[0:1], v[0:1], 0, s[12:13]
	v_lshl_add_u64 v[0:1], v[0:1], 0, v[2:3]
	s_waitcnt lgkmcnt(1)
	global_store_dwordx4 v[0:1], v[8:11], off sc1
	v_add_u32_e32 v0, s38, v96
	v_ashrrev_i32_e32 v1, 31, v0
	v_lshlrev_b64 v[0:1], 14, v[0:1]
	v_lshl_add_u64 v[0:1], s[4:5], 0, v[0:1]
	v_lshl_add_u64 v[0:1], v[0:1], 0, s[12:13]
	v_lshl_add_u64 v[0:1], v[0:1], 0, v[2:3]
	s_waitcnt lgkmcnt(0)
	global_store_dwordx4 v[0:1], v[12:15], off sc1
	v_add_u32_e32 v0, s38, v73
	ds_read_b128 v[8:11], v74
	ds_read_b128 v[12:15], v76
	v_ashrrev_i32_e32 v1, 31, v0
	v_lshlrev_b64 v[0:1], 14, v[0:1]
	v_lshl_add_u64 v[0:1], s[4:5], 0, v[0:1]
	v_lshl_add_u64 v[0:1], v[0:1], 0, s[12:13]
	v_lshl_add_u64 v[0:1], v[0:1], 0, v[2:3]
	s_waitcnt lgkmcnt(1)
	global_store_dwordx4 v[0:1], v[8:11], off sc1
	v_add_u32_e32 v0, s38, v75
	v_ashrrev_i32_e32 v1, 31, v0
	v_lshlrev_b64 v[0:1], 14, v[0:1]
	v_lshl_add_u64 v[0:1], s[4:5], 0, v[0:1]
	v_lshl_add_u64 v[0:1], v[0:1], 0, s[12:13]
	v_lshl_add_u64 v[0:1], v[0:1], 0, v[2:3]
	s_waitcnt lgkmcnt(0)
	global_store_dwordx4 v[0:1], v[12:15], off sc1
	v_add_u32_e32 v0, s38, v77
	ds_read_b128 v[8:11], v78
	ds_read_b128 v[12:15], v80
	v_ashrrev_i32_e32 v1, 31, v0
	v_lshlrev_b64 v[0:1], 14, v[0:1]
	v_lshl_add_u64 v[0:1], s[4:5], 0, v[0:1]
	v_lshl_add_u64 v[0:1], v[0:1], 0, s[12:13]
	v_lshl_add_u64 v[0:1], v[0:1], 0, v[2:3]
	s_waitcnt lgkmcnt(1)
	global_store_dwordx4 v[0:1], v[8:11], off sc1
	v_add_u32_e32 v0, s38, v79
	v_ashrrev_i32_e32 v1, 31, v0
	v_lshlrev_b64 v[0:1], 14, v[0:1]
	v_lshl_add_u64 v[0:1], s[4:5], 0, v[0:1]
	v_lshl_add_u64 v[0:1], v[0:1], 0, s[12:13]
	v_lshl_add_u64 v[0:1], v[0:1], 0, v[2:3]
	s_waitcnt lgkmcnt(0)
	global_store_dwordx4 v[0:1], v[12:15], off sc1
	v_add_u32_e32 v0, s38, v81
	ds_read_b128 v[8:11], v82
	ds_read_b128 v[12:15], v84
	v_ashrrev_i32_e32 v1, 31, v0
	v_lshlrev_b64 v[0:1], 14, v[0:1]
	v_lshl_add_u64 v[0:1], s[4:5], 0, v[0:1]
	v_lshl_add_u64 v[0:1], v[0:1], 0, s[12:13]
	v_lshl_add_u64 v[0:1], v[0:1], 0, v[2:3]
	s_waitcnt lgkmcnt(1)
	global_store_dwordx4 v[0:1], v[8:11], off sc1
	v_add_u32_e32 v0, s38, v83
	v_ashrrev_i32_e32 v1, 31, v0
	v_lshlrev_b64 v[0:1], 14, v[0:1]
	v_lshl_add_u64 v[0:1], s[4:5], 0, v[0:1]
	v_lshl_add_u64 v[0:1], v[0:1], 0, s[12:13]
	v_readlane_b32 s48, v252, 2
	v_lshl_add_u64 v[0:1], v[0:1], 0, v[2:3]
	s_mov_b32 s0, s48
	s_waitcnt lgkmcnt(0)
	global_store_dwordx4 v[0:1], v[12:15], off sc1
	s_barrier
	s_add_i32 s35, s0, s35
	s_movk_i32 s63, 0x210
	s_cmpk_gt_i32 s35, 0x3ff
	s_cbranch_scc1 .LBB0_1258
